# GEMM phases (MRG0, OUT, FFN2 up/down): removed compiler-inserted vmcnt(0) drain before each unit K-loop
# speedup vs baseline: 1.0077x; 1.0076x over previous
; #define PG8_STAGE(bufoff, gbase, voff) do { _Pragma("unroll") for (int _i = 0; _i < 2; ++_i) \
;         __builtin_amdgcn_global_load_lds((const unsigned*)((const char*)(gbase) + (voff)[_i]), (PG8_LAS unsigned*)(lds + (bufoff) + ldsw + _i * 8192), 16, 0, 0); } while (0)
; #define PG8_LDA(dst, b, h) do { _Pragma("unroll") for (int m = 0; m < 4; ++m) _Pragma("unroll") for (int k = 0; k < 2; ++k) dst[m][k] = *(const PG8_LAS bf16x8*)(lds + PG8_SA(b, h) + aoff + m * 2048 + k * 1024); } while (0)
; #define PG8_LDB(dst, b, h) do { _Pragma("unroll") for (int n = 0; n < 2; ++n) _Pragma("unroll") for (int k = 0; k < 2; ++k) dst[n][k] = *(const PG8_LAS bf16x8*)(lds + PG8_SB(b, h) + boff + n * 2048 + k * 1024); } while (0)
; #define PG8_WAIT_V(n) asm volatile("s_waitcnt vmcnt(" #n ")" ::: "memory")
; #define PG8_WAIT_L(n) asm volatile("s_waitcnt lgkmcnt(" #n ")" ::: "memory")
; #define PG8_BAR __builtin_amdgcn_s_barrier()
; #define PG8_SCHED __builtin_amdgcn_sched_barrier(0)
; template <class Epi, class Sched, bool ALIGN_EPI = false, bool SP2 = false>
; __device__ __forceinline__ void gemm_phase(PG8_LAS unsigned char* lds, const Gemm g, const Sched& S, const Epi& E) {
;     ...
;         const bool has_next = S.next(ui + 1, nxt);
;         const char* nA = has_next ? (const char*)g.A + (size_t)nxt.pm * tstep : cA; const char* nB = has_next ? (const char*)g.Bt + (size_t)nxt.pn * tstep : cB;
;         for (int t = 0; t < nt; t += 2) {
;             const bool last = (t == nt - 2);
;             const char* a1 = cA + (size_t)(t + 1) * kstep;
;             const char* a2 = last ? nA : cA + (size_t)(t + 2) * kstep; const char* b2 = last ? nB : cB + (size_t)(t + 2) * kstep;
;             const char* a3 = a2 + kstep; const char* b3 = b2 + kstep;
;             if (last && has_next) S.a_ready(nxt);
;             if constexpr (SP2) {
;             PG8_LDB(B0, 0, 0); PG8_LDB(B1, 0, 1); PG8_SCHED; PG8_LDA(At, 0, 0); PG8_STAGE(PG8_SA(1, 1), a1 + hstep, voffA);
;             PG8_WAIT_V(8); PG8_WAIT_L(0); PG8_BAR; PG8_MMA(0, 0, At, B0); PG8_MMA(0, 1, At, B1); PG8_BAR; PG8_SCHED;
;     ...
; #pragma unroll
;         for (int a = 0; a < 2; ++a)
; #pragma unroll
;             for (int b = 0; b < 2; ++b)
; #pragma unroll
;                 for (int m = 0; m < 4; ++m)
; #pragma unroll
;                     for (int n = 0; n < 2; ++n) acc[a][b][m][n] = (f32x4){0.f, 0.f, 0.f, 0.f};
.LBB0_1077:
	s_ashr_i32 s19, s18, 31
	s_lshl_b64 s[20:21], s[18:19], 19
	v_readlane_b32 s2, v253, 17
	s_add_u32 s20, s2, s20
	v_readlane_b32 s2, v253, 18
	s_addc_u32 s21, s2, s21
	s_and_b64 s[22:23], s[10:11], exec
	s_cselect_b32 s19, s21, s25
	s_cselect_b32 s38, s20, s24
	s_ashr_i32 s17, s16, 31
	s_lshl_b64 s[22:23], s[16:17], 19
	v_readlane_b32 s2, v253, 13
	s_add_u32 s22, s2, s22
	v_readlane_b32 s2, v253, 14
	s_addc_u32 s23, s2, s23
	s_and_b64 s[28:29], s[10:11], exec
	s_cselect_b32 s17, s23, s27
	s_cselect_b32 s39, s22, s26
	s_add_u32 s24, s24, 0x40080
	s_addc_u32 s25, s25, 0
	s_add_u32 s40, s26, 0x100
	v_mov_b32_e32 v0, 0
	s_addc_u32 s41, s27, 0
	s_mov_b32 s42, -2
	v_mov_b32_e32 v1, v0
	v_mov_b32_e32 v2, v0
	v_mov_b32_e32 v3, v0
	v_mov_b32_e32 v4, v0
	v_mov_b32_e32 v5, v0
	v_mov_b32_e32 v6, v0
	v_mov_b32_e32 v7, v0
	v_mov_b32_e32 v12, v0
	v_mov_b32_e32 v13, v0
	v_mov_b32_e32 v14, v0
	v_mov_b32_e32 v15, v0
	v_mov_b32_e32 v20, v0
	v_mov_b32_e32 v21, v0
	v_mov_b32_e32 v22, v0
	v_mov_b32_e32 v23, v0
	v_mov_b32_e32 v28, v0
	v_mov_b32_e32 v29, v0
	v_mov_b32_e32 v30, v0
	v_mov_b32_e32 v31, v0
	v_mov_b32_e32 v36, v0
	v_mov_b32_e32 v37, v0
	v_mov_b32_e32 v38, v0
	v_mov_b32_e32 v39, v0
	v_mov_b32_e32 v44, v0
	v_mov_b32_e32 v45, v0
	v_mov_b32_e32 v46, v0
	v_mov_b32_e32 v47, v0
	v_mov_b32_e32 v52, v0
	v_mov_b32_e32 v53, v0
	v_mov_b32_e32 v54, v0
	v_mov_b32_e32 v55, v0
	v_mov_b32_e32 v8, v0
	v_mov_b32_e32 v9, v0
	v_mov_b32_e32 v10, v0
	v_mov_b32_e32 v11, v0
	v_mov_b32_e32 v16, v0
	v_mov_b32_e32 v17, v0
	v_mov_b32_e32 v18, v0
	v_mov_b32_e32 v19, v0
	v_mov_b32_e32 v24, v0
	v_mov_b32_e32 v25, v0
	v_mov_b32_e32 v26, v0
	v_mov_b32_e32 v27, v0
	v_mov_b32_e32 v32, v0
	v_mov_b32_e32 v33, v0
	v_mov_b32_e32 v34, v0
	v_mov_b32_e32 v35, v0
	v_mov_b32_e32 v40, v0
	v_mov_b32_e32 v41, v0
	v_mov_b32_e32 v42, v0
	v_mov_b32_e32 v43, v0
	v_mov_b32_e32 v48, v0
	v_mov_b32_e32 v49, v0
	v_mov_b32_e32 v50, v0
	v_mov_b32_e32 v51, v0
	v_mov_b32_e32 v56, v0
	v_mov_b32_e32 v57, v0
	v_mov_b32_e32 v58, v0
	v_mov_b32_e32 v59, v0
	v_mov_b32_e32 v60, v0
	v_mov_b32_e32 v61, v0
	v_mov_b32_e32 v62, v0
	v_mov_b32_e32 v63, v0
	v_mov_b32_e32 v64, v0
	v_mov_b32_e32 v65, v0
	v_mov_b32_e32 v66, v0
	v_mov_b32_e32 v67, v0
	v_mov_b32_e32 v68, v0
	v_mov_b32_e32 v69, v0
	v_mov_b32_e32 v70, v0
	v_mov_b32_e32 v71, v0
	v_mov_b32_e32 v76, v0
	v_mov_b32_e32 v77, v0
	v_mov_b32_e32 v78, v0
	v_mov_b32_e32 v79, v0
	v_mov_b32_e32 v84, v0
	v_mov_b32_e32 v85, v0
	v_mov_b32_e32 v86, v0
	v_mov_b32_e32 v87, v0
	v_mov_b32_e32 v92, v0
	v_mov_b32_e32 v93, v0
	v_mov_b32_e32 v94, v0
	v_mov_b32_e32 v95, v0
	v_mov_b32_e32 v100, v0
	v_mov_b32_e32 v101, v0
	v_mov_b32_e32 v102, v0
	v_mov_b32_e32 v103, v0
	v_mov_b32_e32 v104, v0
	v_mov_b32_e32 v105, v0
	v_mov_b32_e32 v106, v0
	v_mov_b32_e32 v107, v0
	v_mov_b32_e32 v112, v0
	v_mov_b32_e32 v113, v0
	v_mov_b32_e32 v114, v0
	v_mov_b32_e32 v115, v0
	v_mov_b32_e32 v72, v0
	v_mov_b32_e32 v73, v0
	v_mov_b32_e32 v74, v0
	v_mov_b32_e32 v75, v0
	v_mov_b32_e32 v80, v0
	v_mov_b32_e32 v81, v0
	v_mov_b32_e32 v82, v0
	v_mov_b32_e32 v83, v0
	v_mov_b32_e32 v88, v0
	v_mov_b32_e32 v89, v0
	v_mov_b32_e32 v90, v0
	v_mov_b32_e32 v91, v0
	v_mov_b32_e32 v96, v0
	v_mov_b32_e32 v97, v0
	v_mov_b32_e32 v98, v0
	v_mov_b32_e32 v99, v0
	v_mov_b32_e32 v108, v0
	v_mov_b32_e32 v109, v0
	v_mov_b32_e32 v110, v0
	v_mov_b32_e32 v111, v0
	v_mov_b32_e32 v116, v0
	v_mov_b32_e32 v117, v0
	v_mov_b32_e32 v118, v0
	v_mov_b32_e32 v119, v0
	v_mov_b32_e32 v120, v0
	v_mov_b32_e32 v121, v0
	v_mov_b32_e32 v122, v0
	v_mov_b32_e32 v123, v0
	v_mov_b32_e32 v124, v0
	v_mov_b32_e32 v125, v0
	v_mov_b32_e32 v126, v0
	v_mov_b32_e32 v127, v0
.LBB0_1078:
	s_add_u32 s26, s24, 0xfffc0080
	s_addc_u32 s27, s25, -1
	s_add_i32 s43, 0, 0x10000
	s_cmp_eq_u32 s42, 12
	s_cselect_b32 s29, s19, s27
	s_cselect_b32 s28, s38, s26
	s_cselect_b32 s27, s17, s41
	s_cselect_b32 s26, s39, s40
	s_add_i32 s46, 0, 0x14000
	v_add_u32_e32 v140, s43, v171
	v_add_u32_e32 v166, s46, v171
	ds_read_b128 v[128:131], v140
	ds_read_b128 v[132:135], v140 offset:1024
	ds_read_b128 v[136:139], v140 offset:2048
	ds_read_b128 v[140:143], v140 offset:3072
	ds_read_b128 v[144:147], v166
	ds_read_b128 v[158:161], v166 offset:1024
	ds_read_b128 v[162:165], v166 offset:2048
	ds_read_b128 v[166:169], v166 offset:3072
	v_lshl_add_u64 v[182:183], s[24:25], 0, v[154:155]
	s_add_i32 m0, s1, 0xc000
	ds_read_b128 v[174:177], v173
	ds_read_b128 v[178:181], v173 offset:1024
	ds_read_b128 v[192:195], v173 offset:2048
	ds_read_b128 v[196:199], v173 offset:3072
	ds_read_b128 v[208:211], v173 offset:4096
	ds_read_b128 v[212:215], v173 offset:5120
	ds_read_b128 v[216:219], v173 offset:6144
	ds_read_b128 v[220:223], v173 offset:7168
	global_load_lds_dwordx4 v[182:183], off
	v_lshl_add_u64 v[182:183], s[24:25], 0, v[156:157]
	s_add_i32 m0, s1, 0xe000
	s_nop 0
	global_load_lds_dwordx4 v[182:183], off
	s_waitcnt vmcnt(8)
	s_waitcnt lgkmcnt(0)
	s_barrier
; #define PG8_STAGE(bufoff, gbase, voff) do { _Pragma("unroll") for (int _i = 0; _i < 2; ++_i) \
;         __builtin_amdgcn_global_load_lds((const unsigned*)((const char*)(gbase) + (voff)[_i]), (PG8_LAS unsigned*)(lds + (bufoff) + ldsw + _i * 8192), 16, 0, 0); } while (0)
; #define PG8_LDA(dst, b, h) do { _Pragma("unroll") for (int m = 0; m < 4; ++m) _Pragma("unroll") for (int k = 0; k < 2; ++k) dst[m][k] = *(const PG8_LAS bf16x8*)(lds + PG8_SA(b, h) + aoff + m * 2048 + k * 1024); } while (0)
; #define PG8_MMA(ai, bj, At, Bt) do { __builtin_amdgcn_s_setprio(1); _Pragma("unroll") for (int m = 0; m < 4; ++m) _Pragma("unroll") for (int n = 0; n < 2; ++n) _Pragma("unroll") for (int k = 0; k < 2; ++k) \
;         acc[ai][bj][m][n] = __builtin_amdgcn_mfma_f32_16x16x32_bf16(Bt[n][k], At[m][k], acc[ai][bj][m][n], 0, 0, 0); __builtin_amdgcn_s_setprio(0); } while (0)
; #define PG8_WAIT_V(n) asm volatile("s_waitcnt vmcnt(" #n ")" ::: "memory")
; #define PG8_WAIT_L(n) asm volatile("s_waitcnt lgkmcnt(" #n ")" ::: "memory")
; #define PG8_BAR __builtin_amdgcn_s_barrier()
; #define PG8_SCHED __builtin_amdgcn_sched_barrier(0)
; template <class Epi, class Sched, bool ALIGN_EPI = false, bool SP2 = false>
; __device__ __forceinline__ void gemm_phase(PG8_LAS unsigned char* lds, const Gemm g, const Sched& S, const Epi& E) {
;     ...
;             PG8_WAIT_V(8); PG8_WAIT_L(0); PG8_BAR; PG8_MMA(0, 0, At, B0); PG8_MMA(0, 1, At, B1); PG8_BAR; PG8_SCHED;
;             PG8_LDA(At, 0, 1); PG8_STAGE(PG8_SB(0, 0), b2, voffB); PG8_STAGE(PG8_SB(0, 1), b2 + hstep, voffB); PG8_STAGE(PG8_SA(0, 0), a2, voffA);
;             PG8_WAIT_V(8); PG8_WAIT_L(0); PG8_BAR; PG8_MMA(1, 0, At, B0); PG8_MMA(1, 1, At, B1); PG8_BAR; PG8_SCHED;
	s_setprio 1
	s_waitcnt lgkmcnt(0)
	v_mfma_f32_16x16x32_bf16 v[124:127], v[128:131], v[174:177], v[124:127]
	v_mfma_f32_16x16x32_bf16 v[120:123], v[136:139], v[174:177], v[120:123]
	v_mfma_f32_16x16x32_bf16 v[116:119], v[128:131], v[192:195], v[116:119]
	v_mfma_f32_16x16x32_bf16 v[108:111], v[136:139], v[192:195], v[108:111]
	v_mfma_f32_16x16x32_bf16 v[96:99], v[128:131], v[208:211], v[96:99]
	v_mfma_f32_16x16x32_bf16 v[88:91], v[136:139], v[208:211], v[88:91]
	v_mfma_f32_16x16x32_bf16 v[80:83], v[128:131], v[216:219], v[80:83]
	v_mfma_f32_16x16x32_bf16 v[72:75], v[136:139], v[216:219], v[72:75]
	v_mfma_f32_16x16x32_bf16 v[124:127], v[132:135], v[178:181], v[124:127]
	v_mfma_f32_16x16x32_bf16 v[120:123], v[140:143], v[178:181], v[120:123]
	v_mfma_f32_16x16x32_bf16 v[116:119], v[132:135], v[196:199], v[116:119]
	v_mfma_f32_16x16x32_bf16 v[108:111], v[140:143], v[196:199], v[108:111]
	v_mfma_f32_16x16x32_bf16 v[96:99], v[132:135], v[212:215], v[96:99]
	v_mfma_f32_16x16x32_bf16 v[88:91], v[140:143], v[212:215], v[88:91]
	v_mfma_f32_16x16x32_bf16 v[80:83], v[132:135], v[220:223], v[80:83]
	v_mfma_f32_16x16x32_bf16 v[72:75], v[140:143], v[220:223], v[72:75]
	s_setprio 0
	s_setprio 1
	v_mfma_f32_16x16x32_bf16 v[112:115], v[144:147], v[174:177], v[112:115]
	v_mfma_f32_16x16x32_bf16 v[104:107], v[162:165], v[174:177], v[104:107]
	v_mfma_f32_16x16x32_bf16 v[100:103], v[144:147], v[192:195], v[100:103]
	v_mfma_f32_16x16x32_bf16 v[92:95], v[162:165], v[192:195], v[92:95]
	v_mfma_f32_16x16x32_bf16 v[84:87], v[144:147], v[208:211], v[84:87]
	v_mfma_f32_16x16x32_bf16 v[76:79], v[162:165], v[208:211], v[76:79]
	v_mfma_f32_16x16x32_bf16 v[68:71], v[144:147], v[216:219], v[68:71]
	v_mfma_f32_16x16x32_bf16 v[64:67], v[162:165], v[216:219], v[64:67]
	v_mfma_f32_16x16x32_bf16 v[112:115], v[158:161], v[178:181], v[112:115]
	v_mfma_f32_16x16x32_bf16 v[104:107], v[166:169], v[178:181], v[104:107]
	v_mfma_f32_16x16x32_bf16 v[100:103], v[158:161], v[196:199], v[100:103]
	v_mfma_f32_16x16x32_bf16 v[92:95], v[166:169], v[196:199], v[92:95]
	v_mfma_f32_16x16x32_bf16 v[84:87], v[158:161], v[212:215], v[84:87]
	v_mfma_f32_16x16x32_bf16 v[76:79], v[166:169], v[212:215], v[76:79]
	v_mfma_f32_16x16x32_bf16 v[68:71], v[158:161], v[220:223], v[68:71]
	v_mfma_f32_16x16x32_bf16 v[64:67], v[166:169], v[220:223], v[64:67]
	s_setprio 0
	s_barrier
	s_add_i32 s43, s43, s0
	v_lshl_add_u64 v[182:183], s[26:27], 0, v[186:187]
	s_mov_b32 m0, s43
	ds_read_b128 v[174:177], v173 offset:16384
	ds_read_b128 v[178:181], v173 offset:17408
	ds_read_b128 v[192:195], v173 offset:18432
	ds_read_b128 v[196:199], v173 offset:19456
	ds_read_b128 v[208:211], v173 offset:20480
	ds_read_b128 v[212:215], v173 offset:21504
	ds_read_b128 v[216:219], v173 offset:22528
	ds_read_b128 v[220:223], v173 offset:23552
	global_load_lds_dwordx4 v[182:183], off
	s_add_i32 m0, s43, 0x2000
	s_add_u32 s44, s26, 0x40000
	v_lshl_add_u64 v[188:189], s[26:27], 0, v[148:149]
	s_addc_u32 s45, s27, 0
	s_add_i32 s43, s46, s0
	global_load_lds_dwordx4 v[188:189], off
	v_lshl_add_u64 v[190:191], s[44:45], 0, v[186:187]
	s_mov_b32 m0, s43
	v_lshl_add_u64 v[224:225], s[28:29], 0, v[150:151]
	global_load_lds_dwordx4 v[190:191], off
	v_lshl_add_u64 v[190:191], s[44:45], 0, v[148:149]
	s_add_i32 m0, s43, 0x2000
	s_nop 0
	global_load_lds_dwordx4 v[190:191], off
	v_lshl_add_u64 v[190:191], s[28:29], 0, v[152:153]
	s_mov_b32 m0, s1
	s_nop 0
	global_load_lds_dwordx4 v[190:191], off
	s_mov_b32 m0, s3
	s_nop 0
	global_load_lds_dwordx4 v[224:225], off
	s_waitcnt vmcnt(8)
	s_waitcnt lgkmcnt(0)
	s_barrier
	s_setprio 1
	s_waitcnt lgkmcnt(0)
	v_mfma_f32_16x16x32_bf16 v[60:63], v[128:131], v[174:177], v[60:63]
	v_mfma_f32_16x16x32_bf16 v[56:59], v[136:139], v[174:177], v[56:59]
	v_mfma_f32_16x16x32_bf16 v[48:51], v[128:131], v[192:195], v[48:51]
	v_mfma_f32_16x16x32_bf16 v[40:43], v[136:139], v[192:195], v[40:43]
	v_mfma_f32_16x16x32_bf16 v[32:35], v[128:131], v[208:211], v[32:35]
	v_mfma_f32_16x16x32_bf16 v[24:27], v[136:139], v[208:211], v[24:27]
	v_mfma_f32_16x16x32_bf16 v[16:19], v[128:131], v[216:219], v[16:19]
	v_mfma_f32_16x16x32_bf16 v[8:11], v[136:139], v[216:219], v[8:11]
	v_mfma_f32_16x16x32_bf16 v[60:63], v[132:135], v[178:181], v[60:63]
	v_mfma_f32_16x16x32_bf16 v[56:59], v[140:143], v[178:181], v[56:59]
	v_mfma_f32_16x16x32_bf16 v[48:51], v[132:135], v[196:199], v[48:51]
	v_mfma_f32_16x16x32_bf16 v[40:43], v[140:143], v[196:199], v[40:43]
	v_mfma_f32_16x16x32_bf16 v[32:35], v[132:135], v[212:215], v[32:35]
	v_mfma_f32_16x16x32_bf16 v[24:27], v[140:143], v[212:215], v[24:27]
	v_mfma_f32_16x16x32_bf16 v[16:19], v[132:135], v[220:223], v[16:19]
	v_mfma_f32_16x16x32_bf16 v[8:11], v[140:143], v[220:223], v[8:11]
	s_setprio 0
	s_setprio 1
	v_mfma_f32_16x16x32_bf16 v[52:55], v[144:147], v[174:177], v[52:55]
	v_mfma_f32_16x16x32_bf16 v[44:47], v[162:165], v[174:177], v[44:47]
	v_mfma_f32_16x16x32_bf16 v[36:39], v[144:147], v[192:195], v[36:39]
	v_mfma_f32_16x16x32_bf16 v[28:31], v[162:165], v[192:195], v[28:31]
	v_mfma_f32_16x16x32_bf16 v[20:23], v[144:147], v[208:211], v[20:23]
	v_mfma_f32_16x16x32_bf16 v[12:15], v[162:165], v[208:211], v[12:15]
	v_mfma_f32_16x16x32_bf16 v[4:7], v[144:147], v[216:219], v[4:7]
	v_mfma_f32_16x16x32_bf16 v[0:3], v[162:165], v[216:219], v[0:3]
	v_mfma_f32_16x16x32_bf16 v[52:55], v[158:161], v[178:181], v[52:55]
	v_mfma_f32_16x16x32_bf16 v[44:47], v[166:169], v[178:181], v[44:47]
	v_mfma_f32_16x16x32_bf16 v[36:39], v[158:161], v[196:199], v[36:39]
	v_mfma_f32_16x16x32_bf16 v[28:31], v[166:169], v[196:199], v[28:31]
	v_mfma_f32_16x16x32_bf16 v[20:23], v[158:161], v[212:215], v[20:23]
	v_mfma_f32_16x16x32_bf16 v[12:15], v[166:169], v[212:215], v[12:15]
	v_mfma_f32_16x16x32_bf16 v[4:7], v[158:161], v[220:223], v[4:7]
	v_mfma_f32_16x16x32_bf16 v[0:3], v[166:169], v[220:223], v[0:3]
	s_setprio 0
	s_barrier
; #define PG8_STAGE(bufoff, gbase, voff) do { _Pragma("unroll") for (int _i = 0; _i < 2; ++_i) \
;         __builtin_amdgcn_global_load_lds((const unsigned*)((const char*)(gbase) + (voff)[_i]), (PG8_LAS unsigned*)(lds + (bufoff) + ldsw + _i * 8192), 16, 0, 0); } while (0)
; #define PG8_LDA(dst, b, h) do { _Pragma("unroll") for (int m = 0; m < 4; ++m) _Pragma("unroll") for (int k = 0; k < 2; ++k) dst[m][k] = *(const PG8_LAS bf16x8*)(lds + PG8_SA(b, h) + aoff + m * 2048 + k * 1024); } while (0)
; #define PG8_LDB(dst, b, h) do { _Pragma("unroll") for (int n = 0; n < 2; ++n) _Pragma("unroll") for (int k = 0; k < 2; ++k) dst[n][k] = *(const PG8_LAS bf16x8*)(lds + PG8_SB(b, h) + boff + n * 2048 + k * 1024); } while (0)
; #define PG8_MMA(ai, bj, At, Bt) do { __builtin_amdgcn_s_setprio(1); _Pragma("unroll") for (int m = 0; m < 4; ++m) _Pragma("unroll") for (int n = 0; n < 2; ++n) _Pragma("unroll") for (int k = 0; k < 2; ++k) \
;         acc[ai][bj][m][n] = __builtin_amdgcn_mfma_f32_16x16x32_bf16(Bt[n][k], At[m][k], acc[ai][bj][m][n], 0, 0, 0); __builtin_amdgcn_s_setprio(0); } while (0)
; #define PG8_WAIT_V(n) asm volatile("s_waitcnt vmcnt(" #n ")" ::: "memory")
; #define PG8_WAIT_L(n) asm volatile("s_waitcnt lgkmcnt(" #n ")" ::: "memory")
; #define PG8_BAR __builtin_amdgcn_s_barrier()
; #define PG8_SCHED __builtin_amdgcn_sched_barrier(0)
; template <class Epi, class Sched, bool ALIGN_EPI = false, bool SP2 = false>
; __device__ __forceinline__ void gemm_phase(PG8_LAS unsigned char* lds, const Gemm g, const Sched& S, const Epi& E) {
;     ...
;             PG8_LDB(B0, 1, 0); PG8_LDB(B1, 1, 1); PG8_SCHED; PG8_LDA(At, 1, 0); PG8_STAGE(PG8_SA(0, 1), a2 + hstep, voffA);
;             PG8_WAIT_V(8); PG8_WAIT_L(0); PG8_BAR; PG8_MMA(0, 0, At, B0); PG8_MMA(0, 1, At, B1); PG8_BAR; PG8_SCHED;
	s_add_i32 s43, 0, 0x18000
	s_add_i32 s44, 0, 0x1c000
	v_add_u32_e32 v140, s43, v171
	v_add_u32_e32 v166, s44, v171
	ds_read_b128 v[128:131], v140
	ds_read_b128 v[132:135], v140 offset:1024
	ds_read_b128 v[136:139], v140 offset:2048
	ds_read_b128 v[140:143], v140 offset:3072
	ds_read_b128 v[144:147], v166
	ds_read_b128 v[158:161], v166 offset:1024
	ds_read_b128 v[162:165], v166 offset:2048
	ds_read_b128 v[166:169], v166 offset:3072
	s_add_u32 s28, s28, 0x40000
	s_addc_u32 s29, s29, 0
	s_mov_b32 m0, s30
	v_lshl_add_u64 v[226:227], s[28:29], 0, v[152:153]
	ds_read_b128 v[174:177], v173 offset:32768
	ds_read_b128 v[178:181], v173 offset:33792
	ds_read_b128 v[192:195], v173 offset:34816
	ds_read_b128 v[196:199], v173 offset:35840
	ds_read_b128 v[208:211], v173 offset:36864
	ds_read_b128 v[212:215], v173 offset:37888
	ds_read_b128 v[216:219], v173 offset:38912
	ds_read_b128 v[220:223], v173 offset:39936
	global_load_lds_dwordx4 v[226:227], off
	v_lshl_add_u64 v[226:227], s[28:29], 0, v[150:151]
	s_mov_b32 m0, s31
	s_nop 0
	global_load_lds_dwordx4 v[226:227], off
	s_waitcnt vmcnt(8)
	s_waitcnt lgkmcnt(0)
	s_barrier
	s_setprio 1
	s_waitcnt lgkmcnt(0)
	v_mfma_f32_16x16x32_bf16 v[124:127], v[128:131], v[174:177], v[124:127]
	v_mfma_f32_16x16x32_bf16 v[120:123], v[136:139], v[174:177], v[120:123]
	v_mfma_f32_16x16x32_bf16 v[116:119], v[128:131], v[192:195], v[116:119]
	v_mfma_f32_16x16x32_bf16 v[108:111], v[136:139], v[192:195], v[108:111]
	v_mfma_f32_16x16x32_bf16 v[96:99], v[128:131], v[208:211], v[96:99]
	v_mfma_f32_16x16x32_bf16 v[88:91], v[136:139], v[208:211], v[88:91]
	v_mfma_f32_16x16x32_bf16 v[80:83], v[128:131], v[216:219], v[80:83]
	v_mfma_f32_16x16x32_bf16 v[72:75], v[136:139], v[216:219], v[72:75]
	v_mfma_f32_16x16x32_bf16 v[124:127], v[132:135], v[178:181], v[124:127]
	v_mfma_f32_16x16x32_bf16 v[120:123], v[140:143], v[178:181], v[120:123]
	v_mfma_f32_16x16x32_bf16 v[116:119], v[132:135], v[196:199], v[116:119]
	v_mfma_f32_16x16x32_bf16 v[108:111], v[140:143], v[196:199], v[108:111]
	v_mfma_f32_16x16x32_bf16 v[96:99], v[132:135], v[212:215], v[96:99]
	v_mfma_f32_16x16x32_bf16 v[88:91], v[140:143], v[212:215], v[88:91]
	v_mfma_f32_16x16x32_bf16 v[80:83], v[132:135], v[220:223], v[80:83]
	v_mfma_f32_16x16x32_bf16 v[72:75], v[140:143], v[220:223], v[72:75]
	s_setprio 0
	s_setprio 1
	v_mfma_f32_16x16x32_bf16 v[112:115], v[144:147], v[174:177], v[112:115]
	v_mfma_f32_16x16x32_bf16 v[104:107], v[162:165], v[174:177], v[104:107]
	v_mfma_f32_16x16x32_bf16 v[100:103], v[144:147], v[192:195], v[100:103]
	v_mfma_f32_16x16x32_bf16 v[92:95], v[162:165], v[192:195], v[92:95]
	v_mfma_f32_16x16x32_bf16 v[84:87], v[144:147], v[208:211], v[84:87]
	v_mfma_f32_16x16x32_bf16 v[76:79], v[162:165], v[208:211], v[76:79]
	v_mfma_f32_16x16x32_bf16 v[68:71], v[144:147], v[216:219], v[68:71]
	v_mfma_f32_16x16x32_bf16 v[64:67], v[162:165], v[216:219], v[64:67]
	v_mfma_f32_16x16x32_bf16 v[112:115], v[158:161], v[178:181], v[112:115]
	v_mfma_f32_16x16x32_bf16 v[104:107], v[166:169], v[178:181], v[104:107]
	v_mfma_f32_16x16x32_bf16 v[100:103], v[158:161], v[196:199], v[100:103]
	v_mfma_f32_16x16x32_bf16 v[92:95], v[166:169], v[196:199], v[92:95]
	v_mfma_f32_16x16x32_bf16 v[84:87], v[158:161], v[212:215], v[84:87]
	v_mfma_f32_16x16x32_bf16 v[76:79], v[166:169], v[212:215], v[76:79]
	v_mfma_f32_16x16x32_bf16 v[68:71], v[158:161], v[220:223], v[68:71]
	v_mfma_f32_16x16x32_bf16 v[64:67], v[166:169], v[220:223], v[64:67]
	s_setprio 0
	s_barrier
; #define PG8_STAGE(bufoff, gbase, voff) do { _Pragma("unroll") for (int _i = 0; _i < 2; ++_i) \
;         __builtin_amdgcn_global_load_lds((const unsigned*)((const char*)(gbase) + (voff)[_i]), (PG8_LAS unsigned*)(lds + (bufoff) + ldsw + _i * 8192), 16, 0, 0); } while (0)
; #define PG8_LDA(dst, b, h) do { _Pragma("unroll") for (int m = 0; m < 4; ++m) _Pragma("unroll") for (int k = 0; k < 2; ++k) dst[m][k] = *(const PG8_LAS bf16x8*)(lds + PG8_SA(b, h) + aoff + m * 2048 + k * 1024); } while (0)
; #define PG8_MMA(ai, bj, At, Bt) do { __builtin_amdgcn_s_setprio(1); _Pragma("unroll") for (int m = 0; m < 4; ++m) _Pragma("unroll") for (int n = 0; n < 2; ++n) _Pragma("unroll") for (int k = 0; k < 2; ++k) \
;         acc[ai][bj][m][n] = __builtin_amdgcn_mfma_f32_16x16x32_bf16(Bt[n][k], At[m][k], acc[ai][bj][m][n], 0, 0, 0); __builtin_amdgcn_s_setprio(0); } while (0)
; #define PG8_WAIT_V(n) asm volatile("s_waitcnt vmcnt(" #n ")" ::: "memory")
; #define PG8_WAIT_L(n) asm volatile("s_waitcnt lgkmcnt(" #n ")" ::: "memory")
; #define PG8_BAR __builtin_amdgcn_s_barrier()
; #define PG8_SCHED __builtin_amdgcn_sched_barrier(0)
; template <class Epi, class Sched, bool ALIGN_EPI = false, bool SP2 = false>
; __device__ __forceinline__ void gemm_phase(PG8_LAS unsigned char* lds, const Gemm g, const Sched& S, const Epi& E) {
;     ...
;             PG8_LDA(At, 1, 1); PG8_STAGE(PG8_SB(1, 0), b3, voffB); PG8_STAGE(PG8_SB(1, 1), b3 + hstep, voffB); PG8_STAGE(PG8_SA(1, 0), a3, voffA);
;             PG8_WAIT_V(8); PG8_WAIT_L(0); PG8_BAR; PG8_MMA(1, 0, At, B0); PG8_MMA(1, 1, At, B1); PG8_BAR; PG8_SCHED;
	s_add_i32 s28, s43, s0
	v_lshl_add_u64 v[182:183], v[182:183], 0, s[92:93]
	s_mov_b32 m0, s28
	ds_read_b128 v[174:177], v173 offset:49152
	ds_read_b128 v[178:181], v173 offset:50176
	ds_read_b128 v[192:195], v173 offset:51200
	ds_read_b128 v[196:199], v173 offset:52224
	ds_read_b128 v[208:211], v173 offset:53248
	ds_read_b128 v[212:215], v173 offset:54272
	ds_read_b128 v[216:219], v173 offset:55296
	ds_read_b128 v[220:223], v173 offset:56320
	global_load_lds_dwordx4 v[182:183], off
	s_add_i32 m0, s28, 0x2000
	s_add_u32 s26, s26, 0x40080
	v_lshl_add_u64 v[182:183], v[188:189], 0, s[92:93]
	s_addc_u32 s27, s27, 0
	s_add_i32 s28, s44, s0
	global_load_lds_dwordx4 v[182:183], off
	v_lshl_add_u64 v[182:183], s[26:27], 0, v[186:187]
	s_mov_b32 m0, s28
	s_nop 0
	global_load_lds_dwordx4 v[182:183], off
	v_lshl_add_u64 v[182:183], s[26:27], 0, v[148:149]
	s_add_i32 m0, s28, 0x2000
	s_nop 0
	global_load_lds_dwordx4 v[182:183], off
	v_lshl_add_u64 v[182:183], v[190:191], 0, s[92:93]
	s_mov_b32 m0, s34
	s_nop 0
	global_load_lds_dwordx4 v[182:183], off
	v_lshl_add_u64 v[182:183], v[224:225], 0, s[92:93]
	s_mov_b32 m0, s35
	s_nop 0
	global_load_lds_dwordx4 v[182:183], off
	s_waitcnt vmcnt(8)
	s_waitcnt lgkmcnt(0)
	s_barrier
	s_setprio 1
	s_waitcnt lgkmcnt(0)
	v_mfma_f32_16x16x32_bf16 v[60:63], v[128:131], v[174:177], v[60:63]
	v_mfma_f32_16x16x32_bf16 v[56:59], v[136:139], v[174:177], v[56:59]
	v_mfma_f32_16x16x32_bf16 v[48:51], v[128:131], v[192:195], v[48:51]
	v_mfma_f32_16x16x32_bf16 v[40:43], v[136:139], v[192:195], v[40:43]
	v_mfma_f32_16x16x32_bf16 v[32:35], v[128:131], v[208:211], v[32:35]
	v_mfma_f32_16x16x32_bf16 v[24:27], v[136:139], v[208:211], v[24:27]
	v_mfma_f32_16x16x32_bf16 v[16:19], v[128:131], v[216:219], v[16:19]
	v_mfma_f32_16x16x32_bf16 v[8:11], v[136:139], v[216:219], v[8:11]
	v_mfma_f32_16x16x32_bf16 v[60:63], v[132:135], v[178:181], v[60:63]
	v_mfma_f32_16x16x32_bf16 v[56:59], v[140:143], v[178:181], v[56:59]
	v_mfma_f32_16x16x32_bf16 v[48:51], v[132:135], v[196:199], v[48:51]
	v_mfma_f32_16x16x32_bf16 v[40:43], v[140:143], v[196:199], v[40:43]
	v_mfma_f32_16x16x32_bf16 v[32:35], v[132:135], v[212:215], v[32:35]
	v_mfma_f32_16x16x32_bf16 v[24:27], v[140:143], v[212:215], v[24:27]
	v_mfma_f32_16x16x32_bf16 v[16:19], v[132:135], v[220:223], v[16:19]
	v_mfma_f32_16x16x32_bf16 v[8:11], v[140:143], v[220:223], v[8:11]
	s_setprio 0
	s_setprio 1
	v_mfma_f32_16x16x32_bf16 v[52:55], v[144:147], v[174:177], v[52:55]
	v_mfma_f32_16x16x32_bf16 v[44:47], v[162:165], v[174:177], v[44:47]
	v_mfma_f32_16x16x32_bf16 v[36:39], v[144:147], v[192:195], v[36:39]
	v_mfma_f32_16x16x32_bf16 v[28:31], v[162:165], v[192:195], v[28:31]
	v_mfma_f32_16x16x32_bf16 v[20:23], v[144:147], v[208:211], v[20:23]
	v_mfma_f32_16x16x32_bf16 v[12:15], v[162:165], v[208:211], v[12:15]
	v_mfma_f32_16x16x32_bf16 v[4:7], v[144:147], v[216:219], v[4:7]
	v_mfma_f32_16x16x32_bf16 v[0:3], v[162:165], v[216:219], v[0:3]
	v_mfma_f32_16x16x32_bf16 v[52:55], v[158:161], v[178:181], v[52:55]
	v_mfma_f32_16x16x32_bf16 v[44:47], v[166:169], v[178:181], v[44:47]
	v_mfma_f32_16x16x32_bf16 v[36:39], v[158:161], v[196:199], v[36:39]
	v_mfma_f32_16x16x32_bf16 v[28:31], v[166:169], v[196:199], v[28:31]
	v_mfma_f32_16x16x32_bf16 v[20:23], v[158:161], v[212:215], v[20:23]
	v_mfma_f32_16x16x32_bf16 v[12:15], v[166:169], v[212:215], v[12:15]
	v_mfma_f32_16x16x32_bf16 v[4:7], v[158:161], v[220:223], v[4:7]
	v_mfma_f32_16x16x32_bf16 v[0:3], v[166:169], v[220:223], v[0:3]
	s_setprio 0
	s_barrier
	s_add_i32 s42, s42, 2
	s_add_u32 s24, s24, 0x100
	s_addc_u32 s25, s25, 0
	s_add_u32 s40, s40, 0x100
	s_addc_u32 s41, s41, 0
	s_cmp_gt_u32 s42, 13
	s_cbranch_scc0 .LBB0_1078
	s_and_b64 vcc, exec, s[14:15]
	s_cbranch_vccz .LBB0_1081
	s_barrier

; #define PG8_STAGE(bufoff, gbase, voff) do { _Pragma("unroll") for (int _i = 0; _i < 2; ++_i) \
;         __builtin_amdgcn_global_load_lds((const unsigned*)((const char*)(gbase) + (voff)[_i]), (PG8_LAS unsigned*)(lds + (bufoff) + ldsw + _i * 8192), 16, 0, 0); } while (0)
; #define PG8_LDA(dst, b, h) do { _Pragma("unroll") for (int m = 0; m < 4; ++m) _Pragma("unroll") for (int k = 0; k < 2; ++k) dst[m][k] = *(const PG8_LAS bf16x8*)(lds + PG8_SA(b, h) + aoff + m * 2048 + k * 1024); } while (0)
; #define PG8_LDB(dst, b, h) do { _Pragma("unroll") for (int n = 0; n < 2; ++n) _Pragma("unroll") for (int k = 0; k < 2; ++k) dst[n][k] = *(const PG8_LAS bf16x8*)(lds + PG8_SB(b, h) + boff + n * 2048 + k * 1024); } while (0)
; #define PG8_WAIT_V(n) asm volatile("s_waitcnt vmcnt(" #n ")" ::: "memory")
; #define PG8_WAIT_L(n) asm volatile("s_waitcnt lgkmcnt(" #n ")" ::: "memory")
; #define PG8_BAR __builtin_amdgcn_s_barrier()
; #define PG8_SCHED __builtin_amdgcn_sched_barrier(0)
; template <class Epi, class Sched, bool ALIGN_EPI = false, bool SP2 = false>
; __device__ __forceinline__ void gemm_phase(PG8_LAS unsigned char* lds, const Gemm g, const Sched& S, const Epi& E) {
;     ...
;         const bool has_next = S.next(ui + 1, nxt);
;         const char* nA = has_next ? (const char*)g.A + (size_t)nxt.pm * tstep : cA; const char* nB = has_next ? (const char*)g.Bt + (size_t)nxt.pn * tstep : cB;
;         for (int t = 0; t < nt; t += 2) {
;             const bool last = (t == nt - 2);
;             const char* a1 = cA + (size_t)(t + 1) * kstep;
;             const char* a2 = last ? nA : cA + (size_t)(t + 2) * kstep; const char* b2 = last ? nB : cB + (size_t)(t + 2) * kstep;
;             const char* a3 = a2 + kstep; const char* b3 = b2 + kstep;
;             if (last && has_next) S.a_ready(nxt);
;             if constexpr (SP2) {
;             PG8_LDB(B0, 0, 0); PG8_LDB(B1, 0, 1); PG8_SCHED; PG8_LDA(At, 0, 0); PG8_STAGE(PG8_SA(1, 1), a1 + hstep, voffA);
;             PG8_WAIT_V(8); PG8_WAIT_L(0); PG8_BAR; PG8_MMA(0, 0, At, B0); PG8_MMA(0, 1, At, B1); PG8_BAR; PG8_SCHED;
;     ...
; #pragma unroll
;         for (int a = 0; a < 2; ++a)
; #pragma unroll
;             for (int b = 0; b < 2; ++b)
; #pragma unroll
;                 for (int m = 0; m < 4; ++m)
; #pragma unroll
;                     for (int n = 0; n < 2; ++n) acc[a][b][m][n] = (f32x4){0.f, 0.f, 0.f, 0.f};
.LBB0_1169:
	s_ashr_i32 s19, s18, 31
	s_lshl_b64 s[20:21], s[18:19], 19
	s_add_u32 s20, s80, s20
	s_addc_u32 s21, s81, s21
	s_and_b64 s[22:23], s[10:11], exec
	s_cselect_b32 s19, s21, s25
	s_cselect_b32 s38, s20, s24
	s_ashr_i32 s17, s16, 31
	s_lshl_b64 s[22:23], s[16:17], 19
	v_readlane_b32 s2, v253, 53
	s_add_u32 s22, s2, s22
	v_readlane_b32 s2, v253, 54
	s_addc_u32 s23, s2, s23
	s_and_b64 s[28:29], s[10:11], exec
	s_cselect_b32 s17, s23, s27
	s_cselect_b32 s39, s22, s26
	s_add_u32 s24, s24, 0x40080
	s_addc_u32 s25, s25, 0
	s_add_u32 s40, s26, 0x100
	v_mov_b32_e32 v0, 0
	s_addc_u32 s41, s27, 0
	s_mov_b32 s42, -2
	v_mov_b32_e32 v1, v0
	v_mov_b32_e32 v2, v0
	v_mov_b32_e32 v3, v0
	v_mov_b32_e32 v4, v0
	v_mov_b32_e32 v5, v0
	v_mov_b32_e32 v6, v0
	v_mov_b32_e32 v7, v0
	v_mov_b32_e32 v16, v0
	v_mov_b32_e32 v17, v0
	v_mov_b32_e32 v18, v0
	v_mov_b32_e32 v19, v0
	v_mov_b32_e32 v20, v0
	v_mov_b32_e32 v21, v0
	v_mov_b32_e32 v22, v0
	v_mov_b32_e32 v23, v0
	v_mov_b32_e32 v32, v0
	v_mov_b32_e32 v33, v0
	v_mov_b32_e32 v34, v0
	v_mov_b32_e32 v35, v0
	v_mov_b32_e32 v36, v0
	v_mov_b32_e32 v37, v0
	v_mov_b32_e32 v38, v0
	v_mov_b32_e32 v39, v0
	v_mov_b32_e32 v48, v0
	v_mov_b32_e32 v49, v0
	v_mov_b32_e32 v50, v0
	v_mov_b32_e32 v51, v0
	v_mov_b32_e32 v52, v0
	v_mov_b32_e32 v53, v0
	v_mov_b32_e32 v54, v0
	v_mov_b32_e32 v55, v0
	v_mov_b32_e32 v8, v0
	v_mov_b32_e32 v9, v0
	v_mov_b32_e32 v10, v0
	v_mov_b32_e32 v11, v0
	v_mov_b32_e32 v12, v0
	v_mov_b32_e32 v13, v0
	v_mov_b32_e32 v14, v0
	v_mov_b32_e32 v15, v0
	v_mov_b32_e32 v24, v0
	v_mov_b32_e32 v25, v0
	v_mov_b32_e32 v26, v0
	v_mov_b32_e32 v27, v0
	v_mov_b32_e32 v28, v0
	v_mov_b32_e32 v29, v0
	v_mov_b32_e32 v30, v0
	v_mov_b32_e32 v31, v0
	v_mov_b32_e32 v40, v0
	v_mov_b32_e32 v41, v0
	v_mov_b32_e32 v42, v0
	v_mov_b32_e32 v43, v0
	v_mov_b32_e32 v44, v0
	v_mov_b32_e32 v45, v0
	v_mov_b32_e32 v46, v0
	v_mov_b32_e32 v47, v0
	v_mov_b32_e32 v56, v0
	v_mov_b32_e32 v57, v0
	v_mov_b32_e32 v58, v0
	v_mov_b32_e32 v59, v0
	v_mov_b32_e32 v60, v0
	v_mov_b32_e32 v61, v0
	v_mov_b32_e32 v62, v0
	v_mov_b32_e32 v63, v0
	v_mov_b32_e32 v64, v0
	v_mov_b32_e32 v65, v0
	v_mov_b32_e32 v66, v0
	v_mov_b32_e32 v67, v0
	v_mov_b32_e32 v68, v0
	v_mov_b32_e32 v69, v0
	v_mov_b32_e32 v70, v0
	v_mov_b32_e32 v71, v0
	v_mov_b32_e32 v80, v0
	v_mov_b32_e32 v81, v0
	v_mov_b32_e32 v82, v0
	v_mov_b32_e32 v83, v0
	v_mov_b32_e32 v84, v0
	v_mov_b32_e32 v85, v0
	v_mov_b32_e32 v86, v0
	v_mov_b32_e32 v87, v0
	v_mov_b32_e32 v96, v0
	v_mov_b32_e32 v97, v0
	v_mov_b32_e32 v98, v0
	v_mov_b32_e32 v99, v0
	v_mov_b32_e32 v100, v0
	v_mov_b32_e32 v101, v0
	v_mov_b32_e32 v102, v0
	v_mov_b32_e32 v103, v0
	v_mov_b32_e32 v112, v0
	v_mov_b32_e32 v113, v0
	v_mov_b32_e32 v114, v0
	v_mov_b32_e32 v115, v0
	v_mov_b32_e32 v116, v0
	v_mov_b32_e32 v117, v0
	v_mov_b32_e32 v118, v0
	v_mov_b32_e32 v119, v0
	v_mov_b32_e32 v72, v0
	v_mov_b32_e32 v73, v0
	v_mov_b32_e32 v74, v0
	v_mov_b32_e32 v75, v0
	v_mov_b32_e32 v76, v0
	v_mov_b32_e32 v77, v0
	v_mov_b32_e32 v78, v0
	v_mov_b32_e32 v79, v0
	v_mov_b32_e32 v88, v0
	v_mov_b32_e32 v89, v0
	v_mov_b32_e32 v90, v0
	v_mov_b32_e32 v91, v0
	v_mov_b32_e32 v92, v0
	v_mov_b32_e32 v93, v0
	v_mov_b32_e32 v94, v0
	v_mov_b32_e32 v95, v0
	v_mov_b32_e32 v104, v0
	v_mov_b32_e32 v105, v0
	v_mov_b32_e32 v106, v0
	v_mov_b32_e32 v107, v0
	v_mov_b32_e32 v108, v0
	v_mov_b32_e32 v109, v0
	v_mov_b32_e32 v110, v0
	v_mov_b32_e32 v111, v0
	v_mov_b32_e32 v120, v0
	v_mov_b32_e32 v121, v0
	v_mov_b32_e32 v122, v0
	v_mov_b32_e32 v123, v0
	v_mov_b32_e32 v124, v0
	v_mov_b32_e32 v125, v0
	v_mov_b32_e32 v126, v0
	v_mov_b32_e32 v127, v0
.LBB0_1170:
	s_add_u32 s26, s24, 0xfffc0080
	s_addc_u32 s27, s25, -1
	s_add_i32 s43, 0, 0x10000
	s_cmp_eq_u32 s42, 12
	s_cselect_b32 s29, s19, s27
	s_cselect_b32 s28, s38, s26
	s_cselect_b32 s27, s17, s41
	s_cselect_b32 s26, s39, s40
	s_add_i32 s46, 0, 0x14000
	v_add_u32_e32 v140, s43, v192
	v_add_u32_e32 v166, s46, v192
	ds_read_b128 v[128:131], v140
	ds_read_b128 v[132:135], v140 offset:1024
	ds_read_b128 v[136:139], v140 offset:2048
	ds_read_b128 v[140:143], v140 offset:3072
	ds_read_b128 v[144:147], v166
	ds_read_b128 v[148:151], v166 offset:1024
	ds_read_b128 v[152:155], v166 offset:2048
	ds_read_b128 v[166:169], v166 offset:3072
	v_lshl_add_u64 v[182:183], s[24:25], 0, v[162:163]
	s_add_i32 m0, s1, 0xc000
	ds_read_b128 v[170:173], v195
	ds_read_b128 v[174:177], v195 offset:1024
	ds_read_b128 v[178:181], v195 offset:2048
	ds_read_b128 v[196:199], v195 offset:3072
	ds_read_b128 v[208:211], v195 offset:4096
	ds_read_b128 v[212:215], v195 offset:5120
	ds_read_b128 v[216:219], v195 offset:6144
	ds_read_b128 v[220:223], v195 offset:7168
	global_load_lds_dwordx4 v[182:183], off
	v_lshl_add_u64 v[182:183], s[24:25], 0, v[164:165]
	s_add_i32 m0, s1, 0xe000
	s_nop 0
	global_load_lds_dwordx4 v[182:183], off
	s_waitcnt vmcnt(8)
	s_waitcnt lgkmcnt(0)
	s_barrier
; #define PG8_STAGE(bufoff, gbase, voff) do { _Pragma("unroll") for (int _i = 0; _i < 2; ++_i) \
;         __builtin_amdgcn_global_load_lds((const unsigned*)((const char*)(gbase) + (voff)[_i]), (PG8_LAS unsigned*)(lds + (bufoff) + ldsw + _i * 8192), 16, 0, 0); } while (0)
; #define PG8_LDA(dst, b, h) do { _Pragma("unroll") for (int m = 0; m < 4; ++m) _Pragma("unroll") for (int k = 0; k < 2; ++k) dst[m][k] = *(const PG8_LAS bf16x8*)(lds + PG8_SA(b, h) + aoff + m * 2048 + k * 1024); } while (0)
; #define PG8_MMA(ai, bj, At, Bt) do { __builtin_amdgcn_s_setprio(1); _Pragma("unroll") for (int m = 0; m < 4; ++m) _Pragma("unroll") for (int n = 0; n < 2; ++n) _Pragma("unroll") for (int k = 0; k < 2; ++k) \
;         acc[ai][bj][m][n] = __builtin_amdgcn_mfma_f32_16x16x32_bf16(Bt[n][k], At[m][k], acc[ai][bj][m][n], 0, 0, 0); __builtin_amdgcn_s_setprio(0); } while (0)
; #define PG8_WAIT_V(n) asm volatile("s_waitcnt vmcnt(" #n ")" ::: "memory")
; #define PG8_WAIT_L(n) asm volatile("s_waitcnt lgkmcnt(" #n ")" ::: "memory")
; #define PG8_BAR __builtin_amdgcn_s_barrier()
; #define PG8_SCHED __builtin_amdgcn_sched_barrier(0)
; template <class Epi, class Sched, bool ALIGN_EPI = false, bool SP2 = false>
; __device__ __forceinline__ void gemm_phase(PG8_LAS unsigned char* lds, const Gemm g, const Sched& S, const Epi& E) {
;     ...
;             PG8_WAIT_V(8); PG8_WAIT_L(0); PG8_BAR; PG8_MMA(0, 0, At, B0); PG8_MMA(0, 1, At, B1); PG8_BAR; PG8_SCHED;
;             PG8_LDA(At, 0, 1); PG8_STAGE(PG8_SB(0, 0), b2, voffB); PG8_STAGE(PG8_SB(0, 1), b2 + hstep, voffB); PG8_STAGE(PG8_SA(0, 0), a2, voffA);
;             PG8_WAIT_V(8); PG8_WAIT_L(0); PG8_BAR; PG8_MMA(1, 0, At, B0); PG8_MMA(1, 1, At, B1); PG8_BAR; PG8_SCHED;
	s_setprio 1
	s_waitcnt lgkmcnt(0)
	v_mfma_f32_16x16x32_bf16 v[124:127], v[128:131], v[170:173], v[124:127]
	v_mfma_f32_16x16x32_bf16 v[120:123], v[136:139], v[170:173], v[120:123]
	v_mfma_f32_16x16x32_bf16 v[108:111], v[128:131], v[178:181], v[108:111]
	v_mfma_f32_16x16x32_bf16 v[104:107], v[136:139], v[178:181], v[104:107]
	v_mfma_f32_16x16x32_bf16 v[92:95], v[128:131], v[208:211], v[92:95]
	v_mfma_f32_16x16x32_bf16 v[88:91], v[136:139], v[208:211], v[88:91]
	v_mfma_f32_16x16x32_bf16 v[76:79], v[128:131], v[216:219], v[76:79]
	v_mfma_f32_16x16x32_bf16 v[72:75], v[136:139], v[216:219], v[72:75]
	v_mfma_f32_16x16x32_bf16 v[124:127], v[132:135], v[174:177], v[124:127]
	v_mfma_f32_16x16x32_bf16 v[120:123], v[140:143], v[174:177], v[120:123]
	v_mfma_f32_16x16x32_bf16 v[108:111], v[132:135], v[196:199], v[108:111]
	v_mfma_f32_16x16x32_bf16 v[104:107], v[140:143], v[196:199], v[104:107]
	v_mfma_f32_16x16x32_bf16 v[92:95], v[132:135], v[212:215], v[92:95]
	v_mfma_f32_16x16x32_bf16 v[88:91], v[140:143], v[212:215], v[88:91]
	v_mfma_f32_16x16x32_bf16 v[76:79], v[132:135], v[220:223], v[76:79]
	v_mfma_f32_16x16x32_bf16 v[72:75], v[140:143], v[220:223], v[72:75]
	s_setprio 0
	s_setprio 1
	v_mfma_f32_16x16x32_bf16 v[116:119], v[144:147], v[170:173], v[116:119]
	v_mfma_f32_16x16x32_bf16 v[112:115], v[152:155], v[170:173], v[112:115]
	v_mfma_f32_16x16x32_bf16 v[100:103], v[144:147], v[178:181], v[100:103]
	v_mfma_f32_16x16x32_bf16 v[96:99], v[152:155], v[178:181], v[96:99]
	v_mfma_f32_16x16x32_bf16 v[84:87], v[144:147], v[208:211], v[84:87]
	v_mfma_f32_16x16x32_bf16 v[80:83], v[152:155], v[208:211], v[80:83]
	v_mfma_f32_16x16x32_bf16 v[68:71], v[144:147], v[216:219], v[68:71]
	v_mfma_f32_16x16x32_bf16 v[64:67], v[152:155], v[216:219], v[64:67]
	v_mfma_f32_16x16x32_bf16 v[116:119], v[148:151], v[174:177], v[116:119]
	v_mfma_f32_16x16x32_bf16 v[112:115], v[166:169], v[174:177], v[112:115]
	v_mfma_f32_16x16x32_bf16 v[100:103], v[148:151], v[196:199], v[100:103]
	v_mfma_f32_16x16x32_bf16 v[96:99], v[166:169], v[196:199], v[96:99]
	v_mfma_f32_16x16x32_bf16 v[84:87], v[148:151], v[212:215], v[84:87]
	v_mfma_f32_16x16x32_bf16 v[80:83], v[166:169], v[212:215], v[80:83]
	v_mfma_f32_16x16x32_bf16 v[68:71], v[148:151], v[220:223], v[68:71]
	v_mfma_f32_16x16x32_bf16 v[64:67], v[166:169], v[220:223], v[64:67]
	s_setprio 0
	s_barrier
	s_add_i32 s43, s43, s0
	v_lshl_add_u64 v[182:183], s[26:27], 0, v[186:187]
	s_mov_b32 m0, s43
	ds_read_b128 v[170:173], v195 offset:16384
	ds_read_b128 v[174:177], v195 offset:17408
	ds_read_b128 v[178:181], v195 offset:18432
	ds_read_b128 v[196:199], v195 offset:19456
	ds_read_b128 v[208:211], v195 offset:20480
	ds_read_b128 v[212:215], v195 offset:21504
	ds_read_b128 v[216:219], v195 offset:22528
	ds_read_b128 v[220:223], v195 offset:23552
	global_load_lds_dwordx4 v[182:183], off
	s_add_i32 m0, s43, 0x2000
	s_add_u32 s44, s26, 0x40000
	v_lshl_add_u64 v[188:189], s[26:27], 0, v[156:157]
	s_addc_u32 s45, s27, 0
	s_add_i32 s43, s46, s0
	global_load_lds_dwordx4 v[188:189], off
	v_lshl_add_u64 v[190:191], s[44:45], 0, v[186:187]
	s_mov_b32 m0, s43
	v_lshl_add_u64 v[224:225], s[28:29], 0, v[158:159]
	global_load_lds_dwordx4 v[190:191], off
	v_lshl_add_u64 v[190:191], s[44:45], 0, v[156:157]
	s_add_i32 m0, s43, 0x2000
	s_nop 0
	global_load_lds_dwordx4 v[190:191], off
	v_lshl_add_u64 v[190:191], s[28:29], 0, v[160:161]
	s_mov_b32 m0, s1
	s_nop 0
	global_load_lds_dwordx4 v[190:191], off
	s_mov_b32 m0, s3
	s_nop 0
	global_load_lds_dwordx4 v[224:225], off
	s_waitcnt vmcnt(8)
	s_waitcnt lgkmcnt(0)
	s_barrier
	s_setprio 1
	s_waitcnt lgkmcnt(0)
	v_mfma_f32_16x16x32_bf16 v[60:63], v[128:131], v[170:173], v[60:63]
	v_mfma_f32_16x16x32_bf16 v[56:59], v[136:139], v[170:173], v[56:59]
	v_mfma_f32_16x16x32_bf16 v[44:47], v[128:131], v[178:181], v[44:47]
	v_mfma_f32_16x16x32_bf16 v[40:43], v[136:139], v[178:181], v[40:43]
	v_mfma_f32_16x16x32_bf16 v[28:31], v[128:131], v[208:211], v[28:31]
	v_mfma_f32_16x16x32_bf16 v[24:27], v[136:139], v[208:211], v[24:27]
	v_mfma_f32_16x16x32_bf16 v[12:15], v[128:131], v[216:219], v[12:15]
	v_mfma_f32_16x16x32_bf16 v[8:11], v[136:139], v[216:219], v[8:11]
	v_mfma_f32_16x16x32_bf16 v[60:63], v[132:135], v[174:177], v[60:63]
	v_mfma_f32_16x16x32_bf16 v[56:59], v[140:143], v[174:177], v[56:59]
	v_mfma_f32_16x16x32_bf16 v[44:47], v[132:135], v[196:199], v[44:47]
	v_mfma_f32_16x16x32_bf16 v[40:43], v[140:143], v[196:199], v[40:43]
	v_mfma_f32_16x16x32_bf16 v[28:31], v[132:135], v[212:215], v[28:31]
	v_mfma_f32_16x16x32_bf16 v[24:27], v[140:143], v[212:215], v[24:27]
	v_mfma_f32_16x16x32_bf16 v[12:15], v[132:135], v[220:223], v[12:15]
	v_mfma_f32_16x16x32_bf16 v[8:11], v[140:143], v[220:223], v[8:11]
	s_setprio 0
	s_setprio 1
	v_mfma_f32_16x16x32_bf16 v[52:55], v[144:147], v[170:173], v[52:55]
	v_mfma_f32_16x16x32_bf16 v[48:51], v[152:155], v[170:173], v[48:51]
	v_mfma_f32_16x16x32_bf16 v[36:39], v[144:147], v[178:181], v[36:39]
	v_mfma_f32_16x16x32_bf16 v[32:35], v[152:155], v[178:181], v[32:35]
	v_mfma_f32_16x16x32_bf16 v[20:23], v[144:147], v[208:211], v[20:23]
	v_mfma_f32_16x16x32_bf16 v[16:19], v[152:155], v[208:211], v[16:19]
	v_mfma_f32_16x16x32_bf16 v[4:7], v[144:147], v[216:219], v[4:7]
	v_mfma_f32_16x16x32_bf16 v[0:3], v[152:155], v[216:219], v[0:3]
	v_mfma_f32_16x16x32_bf16 v[52:55], v[148:151], v[174:177], v[52:55]
	v_mfma_f32_16x16x32_bf16 v[48:51], v[166:169], v[174:177], v[48:51]
	v_mfma_f32_16x16x32_bf16 v[36:39], v[148:151], v[196:199], v[36:39]
	v_mfma_f32_16x16x32_bf16 v[32:35], v[166:169], v[196:199], v[32:35]
	v_mfma_f32_16x16x32_bf16 v[20:23], v[148:151], v[212:215], v[20:23]
	v_mfma_f32_16x16x32_bf16 v[16:19], v[166:169], v[212:215], v[16:19]
	v_mfma_f32_16x16x32_bf16 v[4:7], v[148:151], v[220:223], v[4:7]
	v_mfma_f32_16x16x32_bf16 v[0:3], v[166:169], v[220:223], v[0:3]
	s_setprio 0
	s_barrier
; #define PG8_STAGE(bufoff, gbase, voff) do { _Pragma("unroll") for (int _i = 0; _i < 2; ++_i) \
;         __builtin_amdgcn_global_load_lds((const unsigned*)((const char*)(gbase) + (voff)[_i]), (PG8_LAS unsigned*)(lds + (bufoff) + ldsw + _i * 8192), 16, 0, 0); } while (0)
; #define PG8_LDA(dst, b, h) do { _Pragma("unroll") for (int m = 0; m < 4; ++m) _Pragma("unroll") for (int k = 0; k < 2; ++k) dst[m][k] = *(const PG8_LAS bf16x8*)(lds + PG8_SA(b, h) + aoff + m * 2048 + k * 1024); } while (0)
; #define PG8_LDB(dst, b, h) do { _Pragma("unroll") for (int n = 0; n < 2; ++n) _Pragma("unroll") for (int k = 0; k < 2; ++k) dst[n][k] = *(const PG8_LAS bf16x8*)(lds + PG8_SB(b, h) + boff + n * 2048 + k * 1024); } while (0)
; #define PG8_MMA(ai, bj, At, Bt) do { __builtin_amdgcn_s_setprio(1); _Pragma("unroll") for (int m = 0; m < 4; ++m) _Pragma("unroll") for (int n = 0; n < 2; ++n) _Pragma("unroll") for (int k = 0; k < 2; ++k) \
;         acc[ai][bj][m][n] = __builtin_amdgcn_mfma_f32_16x16x32_bf16(Bt[n][k], At[m][k], acc[ai][bj][m][n], 0, 0, 0); __builtin_amdgcn_s_setprio(0); } while (0)
; #define PG8_WAIT_V(n) asm volatile("s_waitcnt vmcnt(" #n ")" ::: "memory")
; #define PG8_WAIT_L(n) asm volatile("s_waitcnt lgkmcnt(" #n ")" ::: "memory")
; #define PG8_BAR __builtin_amdgcn_s_barrier()
; #define PG8_SCHED __builtin_amdgcn_sched_barrier(0)
; template <class Epi, class Sched, bool ALIGN_EPI = false, bool SP2 = false>
; __device__ __forceinline__ void gemm_phase(PG8_LAS unsigned char* lds, const Gemm g, const Sched& S, const Epi& E) {
;     ...
;             PG8_LDB(B0, 1, 0); PG8_LDB(B1, 1, 1); PG8_SCHED; PG8_LDA(At, 1, 0); PG8_STAGE(PG8_SA(0, 1), a2 + hstep, voffA);
;             PG8_WAIT_V(8); PG8_WAIT_L(0); PG8_BAR; PG8_MMA(0, 0, At, B0); PG8_MMA(0, 1, At, B1); PG8_BAR; PG8_SCHED;
	s_add_i32 s43, 0, 0x18000
	s_add_i32 s44, 0, 0x1c000
	v_add_u32_e32 v140, s43, v192
	v_add_u32_e32 v166, s44, v192
	ds_read_b128 v[128:131], v140
	ds_read_b128 v[132:135], v140 offset:1024
	ds_read_b128 v[136:139], v140 offset:2048
	ds_read_b128 v[140:143], v140 offset:3072
	ds_read_b128 v[144:147], v166
	ds_read_b128 v[148:151], v166 offset:1024
	ds_read_b128 v[152:155], v166 offset:2048
	ds_read_b128 v[166:169], v166 offset:3072
	s_add_u32 s28, s28, 0x40000
	s_addc_u32 s29, s29, 0
	s_mov_b32 m0, s30
	v_lshl_add_u64 v[226:227], s[28:29], 0, v[160:161]
	ds_read_b128 v[170:173], v195 offset:32768
	ds_read_b128 v[174:177], v195 offset:33792
	ds_read_b128 v[178:181], v195 offset:34816
	ds_read_b128 v[196:199], v195 offset:35840
	ds_read_b128 v[208:211], v195 offset:36864
	ds_read_b128 v[212:215], v195 offset:37888
	ds_read_b128 v[216:219], v195 offset:38912
	ds_read_b128 v[220:223], v195 offset:39936
	global_load_lds_dwordx4 v[226:227], off
	v_lshl_add_u64 v[226:227], s[28:29], 0, v[158:159]
	s_mov_b32 m0, s31
	s_nop 0
	global_load_lds_dwordx4 v[226:227], off
	s_waitcnt vmcnt(8)
	s_waitcnt lgkmcnt(0)
	s_barrier
	s_setprio 1
	s_waitcnt lgkmcnt(0)
	v_mfma_f32_16x16x32_bf16 v[124:127], v[128:131], v[170:173], v[124:127]
	v_mfma_f32_16x16x32_bf16 v[120:123], v[136:139], v[170:173], v[120:123]
	v_mfma_f32_16x16x32_bf16 v[108:111], v[128:131], v[178:181], v[108:111]
	v_mfma_f32_16x16x32_bf16 v[104:107], v[136:139], v[178:181], v[104:107]
	v_mfma_f32_16x16x32_bf16 v[92:95], v[128:131], v[208:211], v[92:95]
	v_mfma_f32_16x16x32_bf16 v[88:91], v[136:139], v[208:211], v[88:91]
	v_mfma_f32_16x16x32_bf16 v[76:79], v[128:131], v[216:219], v[76:79]
	v_mfma_f32_16x16x32_bf16 v[72:75], v[136:139], v[216:219], v[72:75]
	v_mfma_f32_16x16x32_bf16 v[124:127], v[132:135], v[174:177], v[124:127]
	v_mfma_f32_16x16x32_bf16 v[120:123], v[140:143], v[174:177], v[120:123]
	v_mfma_f32_16x16x32_bf16 v[108:111], v[132:135], v[196:199], v[108:111]
	v_mfma_f32_16x16x32_bf16 v[104:107], v[140:143], v[196:199], v[104:107]
	v_mfma_f32_16x16x32_bf16 v[92:95], v[132:135], v[212:215], v[92:95]
	v_mfma_f32_16x16x32_bf16 v[88:91], v[140:143], v[212:215], v[88:91]
	v_mfma_f32_16x16x32_bf16 v[76:79], v[132:135], v[220:223], v[76:79]
	v_mfma_f32_16x16x32_bf16 v[72:75], v[140:143], v[220:223], v[72:75]
	s_setprio 0
	s_setprio 1
	v_mfma_f32_16x16x32_bf16 v[116:119], v[144:147], v[170:173], v[116:119]
	v_mfma_f32_16x16x32_bf16 v[112:115], v[152:155], v[170:173], v[112:115]
	v_mfma_f32_16x16x32_bf16 v[100:103], v[144:147], v[178:181], v[100:103]
	v_mfma_f32_16x16x32_bf16 v[96:99], v[152:155], v[178:181], v[96:99]
	v_mfma_f32_16x16x32_bf16 v[84:87], v[144:147], v[208:211], v[84:87]
	v_mfma_f32_16x16x32_bf16 v[80:83], v[152:155], v[208:211], v[80:83]
	v_mfma_f32_16x16x32_bf16 v[68:71], v[144:147], v[216:219], v[68:71]
	v_mfma_f32_16x16x32_bf16 v[64:67], v[152:155], v[216:219], v[64:67]
	v_mfma_f32_16x16x32_bf16 v[116:119], v[148:151], v[174:177], v[116:119]
	v_mfma_f32_16x16x32_bf16 v[112:115], v[166:169], v[174:177], v[112:115]
	v_mfma_f32_16x16x32_bf16 v[100:103], v[148:151], v[196:199], v[100:103]
	v_mfma_f32_16x16x32_bf16 v[96:99], v[166:169], v[196:199], v[96:99]
	v_mfma_f32_16x16x32_bf16 v[84:87], v[148:151], v[212:215], v[84:87]
	v_mfma_f32_16x16x32_bf16 v[80:83], v[166:169], v[212:215], v[80:83]
	v_mfma_f32_16x16x32_bf16 v[68:71], v[148:151], v[220:223], v[68:71]
	v_mfma_f32_16x16x32_bf16 v[64:67], v[166:169], v[220:223], v[64:67]
	s_setprio 0
	s_barrier
; #define PG8_STAGE(bufoff, gbase, voff) do { _Pragma("unroll") for (int _i = 0; _i < 2; ++_i) \
;         __builtin_amdgcn_global_load_lds((const unsigned*)((const char*)(gbase) + (voff)[_i]), (PG8_LAS unsigned*)(lds + (bufoff) + ldsw + _i * 8192), 16, 0, 0); } while (0)
; #define PG8_LDA(dst, b, h) do { _Pragma("unroll") for (int m = 0; m < 4; ++m) _Pragma("unroll") for (int k = 0; k < 2; ++k) dst[m][k] = *(const PG8_LAS bf16x8*)(lds + PG8_SA(b, h) + aoff + m * 2048 + k * 1024); } while (0)
; #define PG8_MMA(ai, bj, At, Bt) do { __builtin_amdgcn_s_setprio(1); _Pragma("unroll") for (int m = 0; m < 4; ++m) _Pragma("unroll") for (int n = 0; n < 2; ++n) _Pragma("unroll") for (int k = 0; k < 2; ++k) \
;         acc[ai][bj][m][n] = __builtin_amdgcn_mfma_f32_16x16x32_bf16(Bt[n][k], At[m][k], acc[ai][bj][m][n], 0, 0, 0); __builtin_amdgcn_s_setprio(0); } while (0)
; #define PG8_WAIT_V(n) asm volatile("s_waitcnt vmcnt(" #n ")" ::: "memory")
; #define PG8_WAIT_L(n) asm volatile("s_waitcnt lgkmcnt(" #n ")" ::: "memory")
; #define PG8_BAR __builtin_amdgcn_s_barrier()
; #define PG8_SCHED __builtin_amdgcn_sched_barrier(0)
; template <class Epi, class Sched, bool ALIGN_EPI = false, bool SP2 = false>
; __device__ __forceinline__ void gemm_phase(PG8_LAS unsigned char* lds, const Gemm g, const Sched& S, const Epi& E) {
;     ...
;             PG8_LDA(At, 1, 1); PG8_STAGE(PG8_SB(1, 0), b3, voffB); PG8_STAGE(PG8_SB(1, 1), b3 + hstep, voffB); PG8_STAGE(PG8_SA(1, 0), a3, voffA);
;             PG8_WAIT_V(8); PG8_WAIT_L(0); PG8_BAR; PG8_MMA(1, 0, At, B0); PG8_MMA(1, 1, At, B1); PG8_BAR; PG8_SCHED;
	s_add_i32 s28, s43, s0
	v_lshl_add_u64 v[182:183], v[182:183], 0, s[92:93]
	s_mov_b32 m0, s28
	ds_read_b128 v[170:173], v195 offset:49152
	ds_read_b128 v[174:177], v195 offset:50176
	ds_read_b128 v[178:181], v195 offset:51200
	ds_read_b128 v[196:199], v195 offset:52224
	ds_read_b128 v[208:211], v195 offset:53248
	ds_read_b128 v[212:215], v195 offset:54272
	ds_read_b128 v[216:219], v195 offset:55296
	ds_read_b128 v[220:223], v195 offset:56320
	global_load_lds_dwordx4 v[182:183], off
	s_add_i32 m0, s28, 0x2000
	s_add_u32 s26, s26, 0x40080
	v_lshl_add_u64 v[182:183], v[188:189], 0, s[92:93]
	s_addc_u32 s27, s27, 0
	s_add_i32 s28, s44, s0
	global_load_lds_dwordx4 v[182:183], off
	v_lshl_add_u64 v[182:183], s[26:27], 0, v[186:187]
	s_mov_b32 m0, s28
	s_nop 0
	global_load_lds_dwordx4 v[182:183], off
	v_lshl_add_u64 v[182:183], s[26:27], 0, v[156:157]
	s_add_i32 m0, s28, 0x2000
	s_nop 0
	global_load_lds_dwordx4 v[182:183], off
	v_lshl_add_u64 v[182:183], v[190:191], 0, s[92:93]
	s_mov_b32 m0, s34
	s_nop 0
	global_load_lds_dwordx4 v[182:183], off
	v_lshl_add_u64 v[182:183], v[224:225], 0, s[92:93]
	s_mov_b32 m0, s35
	s_nop 0
	global_load_lds_dwordx4 v[182:183], off
	s_waitcnt vmcnt(8)
	s_waitcnt lgkmcnt(0)
	s_barrier
	s_setprio 1
	s_waitcnt lgkmcnt(0)
	v_mfma_f32_16x16x32_bf16 v[60:63], v[128:131], v[170:173], v[60:63]
	v_mfma_f32_16x16x32_bf16 v[56:59], v[136:139], v[170:173], v[56:59]
	v_mfma_f32_16x16x32_bf16 v[44:47], v[128:131], v[178:181], v[44:47]
	v_mfma_f32_16x16x32_bf16 v[40:43], v[136:139], v[178:181], v[40:43]
	v_mfma_f32_16x16x32_bf16 v[28:31], v[128:131], v[208:211], v[28:31]
	v_mfma_f32_16x16x32_bf16 v[24:27], v[136:139], v[208:211], v[24:27]
	v_mfma_f32_16x16x32_bf16 v[12:15], v[128:131], v[216:219], v[12:15]
	v_mfma_f32_16x16x32_bf16 v[8:11], v[136:139], v[216:219], v[8:11]
	v_mfma_f32_16x16x32_bf16 v[60:63], v[132:135], v[174:177], v[60:63]
	v_mfma_f32_16x16x32_bf16 v[56:59], v[140:143], v[174:177], v[56:59]
	v_mfma_f32_16x16x32_bf16 v[44:47], v[132:135], v[196:199], v[44:47]
	v_mfma_f32_16x16x32_bf16 v[40:43], v[140:143], v[196:199], v[40:43]
	v_mfma_f32_16x16x32_bf16 v[28:31], v[132:135], v[212:215], v[28:31]
	v_mfma_f32_16x16x32_bf16 v[24:27], v[140:143], v[212:215], v[24:27]
	v_mfma_f32_16x16x32_bf16 v[12:15], v[132:135], v[220:223], v[12:15]
	v_mfma_f32_16x16x32_bf16 v[8:11], v[140:143], v[220:223], v[8:11]
	s_setprio 0
	s_setprio 1
	v_mfma_f32_16x16x32_bf16 v[52:55], v[144:147], v[170:173], v[52:55]
	v_mfma_f32_16x16x32_bf16 v[48:51], v[152:155], v[170:173], v[48:51]
	v_mfma_f32_16x16x32_bf16 v[36:39], v[144:147], v[178:181], v[36:39]
	v_mfma_f32_16x16x32_bf16 v[32:35], v[152:155], v[178:181], v[32:35]
	v_mfma_f32_16x16x32_bf16 v[20:23], v[144:147], v[208:211], v[20:23]
	v_mfma_f32_16x16x32_bf16 v[16:19], v[152:155], v[208:211], v[16:19]
	v_mfma_f32_16x16x32_bf16 v[4:7], v[144:147], v[216:219], v[4:7]
	v_mfma_f32_16x16x32_bf16 v[0:3], v[152:155], v[216:219], v[0:3]
	v_mfma_f32_16x16x32_bf16 v[52:55], v[148:151], v[174:177], v[52:55]
	v_mfma_f32_16x16x32_bf16 v[48:51], v[166:169], v[174:177], v[48:51]
	v_mfma_f32_16x16x32_bf16 v[36:39], v[148:151], v[196:199], v[36:39]
	v_mfma_f32_16x16x32_bf16 v[32:35], v[166:169], v[196:199], v[32:35]
	v_mfma_f32_16x16x32_bf16 v[20:23], v[148:151], v[212:215], v[20:23]
	v_mfma_f32_16x16x32_bf16 v[16:19], v[166:169], v[212:215], v[16:19]
	v_mfma_f32_16x16x32_bf16 v[4:7], v[148:151], v[220:223], v[4:7]
	v_mfma_f32_16x16x32_bf16 v[0:3], v[166:169], v[220:223], v[0:3]
	s_setprio 0
	s_barrier
	s_add_i32 s42, s42, 2
	s_add_u32 s24, s24, 0x100
	s_addc_u32 s25, s25, 0
	s_add_u32 s40, s40, 0x100
	s_addc_u32 s41, s41, 0
	s_cmp_gt_u32 s42, 13
	s_cbranch_scc0 .LBB0_1170
	s_and_b64 vcc, exec, s[14:15]
	s_cbranch_vccz .LBB0_1173
	s_barrier

; #define PG8_STAGE(bufoff, gbase, voff) do { _Pragma("unroll") for (int _i = 0; _i < 2; ++_i) \
;         __builtin_amdgcn_global_load_lds((const unsigned*)((const char*)(gbase) + (voff)[_i]), (PG8_LAS unsigned*)(lds + (bufoff) + ldsw + _i * 8192), 16, 0, 0); } while (0)
; #define PG8_LDA(dst, b, h) do { _Pragma("unroll") for (int m = 0; m < 4; ++m) _Pragma("unroll") for (int k = 0; k < 2; ++k) dst[m][k] = *(const PG8_LAS bf16x8*)(lds + PG8_SA(b, h) + aoff + m * 2048 + k * 1024); } while (0)
; #define PG8_LDB(dst, b, h) do { _Pragma("unroll") for (int n = 0; n < 2; ++n) _Pragma("unroll") for (int k = 0; k < 2; ++k) dst[n][k] = *(const PG8_LAS bf16x8*)(lds + PG8_SB(b, h) + boff + n * 2048 + k * 1024); } while (0)
; #define PG8_WAIT_V(n) asm volatile("s_waitcnt vmcnt(" #n ")" ::: "memory")
; #define PG8_WAIT_L(n) asm volatile("s_waitcnt lgkmcnt(" #n ")" ::: "memory")
; #define PG8_BAR __builtin_amdgcn_s_barrier()
; #define PG8_SCHED __builtin_amdgcn_sched_barrier(0)
; template <class Epi, class Sched, bool ALIGN_EPI = false, bool SP2 = false>
; __device__ __forceinline__ void gemm_phase(PG8_LAS unsigned char* lds, const Gemm g, const Sched& S, const Epi& E) {
;     ...
;         const bool has_next = S.next(ui + 1, nxt);
;         const char* nA = has_next ? (const char*)g.A + (size_t)nxt.pm * tstep : cA; const char* nB = has_next ? (const char*)g.Bt + (size_t)nxt.pn * tstep : cB;
;         for (int t = 0; t < nt; t += 2) {
;             const bool last = (t == nt - 2);
;             const char* a1 = cA + (size_t)(t + 1) * kstep;
;             const char* a2 = last ? nA : cA + (size_t)(t + 2) * kstep; const char* b2 = last ? nB : cB + (size_t)(t + 2) * kstep;
;             const char* a3 = a2 + kstep; const char* b3 = b2 + kstep;
;             if (last && has_next) S.a_ready(nxt);
;             if constexpr (SP2) {
;             PG8_LDB(B0, 0, 0); PG8_LDB(B1, 0, 1); PG8_SCHED; PG8_LDA(At, 0, 0); PG8_STAGE(PG8_SA(1, 1), a1 + hstep, voffA);
;             PG8_WAIT_V(8); PG8_WAIT_L(0); PG8_BAR; PG8_MMA(0, 0, At, B0); PG8_MMA(0, 1, At, B1); PG8_BAR; PG8_SCHED;
;     ...
; #pragma unroll
;         for (int a = 0; a < 2; ++a)
; #pragma unroll
;             for (int b = 0; b < 2; ++b)
; #pragma unroll
;                 for (int m = 0; m < 4; ++m)
; #pragma unroll
;                     for (int n = 0; n < 2; ++n) acc[a][b][m][n] = (f32x4){0.f, 0.f, 0.f, 0.f};
.LBB0_1252:
	s_ashr_i32 s15, s14, 31
	s_lshl_b64 s[16:17], s[14:15], 19
	s_add_u32 s16, s72, s16
	s_addc_u32 s17, s73, s17
	s_and_b64 s[18:19], s[8:9], exec
	s_cselect_b32 s15, s17, s21
	s_cselect_b32 s40, s16, s20
	s_ashr_i32 s13, s12, 31
	s_lshl_b64 s[18:19], s[12:13], 19
	s_add_u32 s18, s2, s18
	s_addc_u32 s19, s3, s19
	s_and_b64 s[24:25], s[8:9], exec
	s_cselect_b32 s13, s19, s23
	s_cselect_b32 s41, s18, s22
	s_add_u32 s20, s20, 0x40080
	s_addc_u32 s21, s21, 0
	s_add_u32 s42, s22, 0x100
	v_mov_b32_e32 v0, 0
	s_addc_u32 s43, s23, 0
	s_mov_b32 s44, -2
	v_mov_b32_e32 v1, v0
	v_mov_b32_e32 v2, v0
	v_mov_b32_e32 v3, v0
	v_mov_b32_e32 v4, v0
	v_mov_b32_e32 v5, v0
	v_mov_b32_e32 v6, v0
	v_mov_b32_e32 v7, v0
	v_mov_b32_e32 v16, v0
	v_mov_b32_e32 v17, v0
	v_mov_b32_e32 v18, v0
	v_mov_b32_e32 v19, v0
	v_mov_b32_e32 v20, v0
	v_mov_b32_e32 v21, v0
	v_mov_b32_e32 v22, v0
	v_mov_b32_e32 v23, v0
	v_mov_b32_e32 v32, v0
	v_mov_b32_e32 v33, v0
	v_mov_b32_e32 v34, v0
	v_mov_b32_e32 v35, v0
	v_mov_b32_e32 v36, v0
	v_mov_b32_e32 v37, v0
	v_mov_b32_e32 v38, v0
	v_mov_b32_e32 v39, v0
	v_mov_b32_e32 v48, v0
	v_mov_b32_e32 v49, v0
	v_mov_b32_e32 v50, v0
	v_mov_b32_e32 v51, v0
	v_mov_b32_e32 v52, v0
	v_mov_b32_e32 v53, v0
	v_mov_b32_e32 v54, v0
	v_mov_b32_e32 v55, v0
	v_mov_b32_e32 v8, v0
	v_mov_b32_e32 v9, v0
	v_mov_b32_e32 v10, v0
	v_mov_b32_e32 v11, v0
	v_mov_b32_e32 v12, v0
	v_mov_b32_e32 v13, v0
	v_mov_b32_e32 v14, v0
	v_mov_b32_e32 v15, v0
	v_mov_b32_e32 v24, v0
	v_mov_b32_e32 v25, v0
	v_mov_b32_e32 v26, v0
	v_mov_b32_e32 v27, v0
	v_mov_b32_e32 v28, v0
	v_mov_b32_e32 v29, v0
	v_mov_b32_e32 v30, v0
	v_mov_b32_e32 v31, v0
	v_mov_b32_e32 v40, v0
	v_mov_b32_e32 v41, v0
	v_mov_b32_e32 v42, v0
	v_mov_b32_e32 v43, v0
	v_mov_b32_e32 v44, v0
	v_mov_b32_e32 v45, v0
	v_mov_b32_e32 v46, v0
	v_mov_b32_e32 v47, v0
	v_mov_b32_e32 v56, v0
	v_mov_b32_e32 v57, v0
	v_mov_b32_e32 v58, v0
	v_mov_b32_e32 v59, v0
	v_mov_b32_e32 v60, v0
	v_mov_b32_e32 v61, v0
	v_mov_b32_e32 v62, v0
	v_mov_b32_e32 v63, v0
	v_mov_b32_e32 v64, v0
	v_mov_b32_e32 v65, v0
	v_mov_b32_e32 v66, v0
	v_mov_b32_e32 v67, v0
	v_mov_b32_e32 v68, v0
	v_mov_b32_e32 v69, v0
	v_mov_b32_e32 v70, v0
	v_mov_b32_e32 v71, v0
	v_mov_b32_e32 v80, v0
	v_mov_b32_e32 v81, v0
	v_mov_b32_e32 v82, v0
	v_mov_b32_e32 v83, v0
	v_mov_b32_e32 v84, v0
	v_mov_b32_e32 v85, v0
	v_mov_b32_e32 v86, v0
	v_mov_b32_e32 v87, v0
	v_mov_b32_e32 v96, v0
	v_mov_b32_e32 v97, v0
	v_mov_b32_e32 v98, v0
	v_mov_b32_e32 v99, v0
	v_mov_b32_e32 v100, v0
	v_mov_b32_e32 v101, v0
	v_mov_b32_e32 v102, v0
	v_mov_b32_e32 v103, v0
	v_mov_b32_e32 v108, v0
	v_mov_b32_e32 v109, v0
	v_mov_b32_e32 v110, v0
	v_mov_b32_e32 v111, v0
	v_mov_b32_e32 v112, v0
	v_mov_b32_e32 v113, v0
	v_mov_b32_e32 v114, v0
	v_mov_b32_e32 v115, v0
	v_mov_b32_e32 v72, v0
	v_mov_b32_e32 v73, v0
	v_mov_b32_e32 v74, v0
	v_mov_b32_e32 v75, v0
	v_mov_b32_e32 v76, v0
	v_mov_b32_e32 v77, v0
	v_mov_b32_e32 v78, v0
	v_mov_b32_e32 v79, v0
	v_mov_b32_e32 v88, v0
	v_mov_b32_e32 v89, v0
	v_mov_b32_e32 v90, v0
	v_mov_b32_e32 v91, v0
	v_mov_b32_e32 v92, v0
	v_mov_b32_e32 v93, v0
	v_mov_b32_e32 v94, v0
	v_mov_b32_e32 v95, v0
	v_mov_b32_e32 v104, v0
	v_mov_b32_e32 v105, v0
	v_mov_b32_e32 v106, v0
	v_mov_b32_e32 v107, v0
	v_mov_b32_e32 v116, v0
	v_mov_b32_e32 v117, v0
	v_mov_b32_e32 v118, v0
	v_mov_b32_e32 v119, v0
	v_mov_b32_e32 v120, v0
	v_mov_b32_e32 v121, v0
	v_mov_b32_e32 v122, v0
	v_mov_b32_e32 v123, v0
	v_mov_b32_e32 v124, v0
	v_mov_b32_e32 v125, v0
	v_mov_b32_e32 v126, v0
	v_mov_b32_e32 v127, v0
.LBB0_1253:
	ds_read_b128 v[144:147], v153
	ds_read_b128 v[158:161], v153 offset:1024
	ds_read_b128 v[162:165], v153 offset:2048
	ds_read_b128 v[166:169], v153 offset:3072
	ds_read_b128 v[170:173], v154
	ds_read_b128 v[174:177], v154 offset:1024
	ds_read_b128 v[178:181], v154 offset:2048
	ds_read_b128 v[182:185], v154 offset:3072
	s_add_u32 s22, s20, 0xfffc0080
	s_addc_u32 s23, s21, -1
	s_cmp_eq_u32 s44, 12
	s_cselect_b32 s25, s15, s23
	s_cselect_b32 s24, s40, s22
	s_cselect_b32 s23, s13, s43
	s_cselect_b32 s22, s41, s42
	v_lshl_add_u64 v[148:149], s[20:21], 0, v[136:137]
	s_add_i32 m0, s28, 0xc000
	ds_read_b128 v[186:189], v155
	ds_read_b128 v[190:193], v155 offset:1024
	ds_read_b128 v[194:197], v155 offset:2048
	ds_read_b128 v[204:207], v155 offset:3072
	ds_read_b128 v[208:211], v155 offset:4096
	ds_read_b128 v[212:215], v155 offset:5120
	ds_read_b128 v[216:219], v155 offset:6144
	ds_read_b128 v[220:223], v155 offset:7168
	global_load_lds_dwordx4 v[148:149], off
	v_lshl_add_u64 v[148:149], s[20:21], 0, v[138:139]
	s_add_i32 m0, s28, 0xe000
	s_nop 0
	global_load_lds_dwordx4 v[148:149], off
	s_waitcnt vmcnt(8)
	s_waitcnt lgkmcnt(0)
	s_barrier
; #define PG8_STAGE(bufoff, gbase, voff) do { _Pragma("unroll") for (int _i = 0; _i < 2; ++_i) \
;         __builtin_amdgcn_global_load_lds((const unsigned*)((const char*)(gbase) + (voff)[_i]), (PG8_LAS unsigned*)(lds + (bufoff) + ldsw + _i * 8192), 16, 0, 0); } while (0)
; #define PG8_LDA(dst, b, h) do { _Pragma("unroll") for (int m = 0; m < 4; ++m) _Pragma("unroll") for (int k = 0; k < 2; ++k) dst[m][k] = *(const PG8_LAS bf16x8*)(lds + PG8_SA(b, h) + aoff + m * 2048 + k * 1024); } while (0)
; #define PG8_MMA(ai, bj, At, Bt) do { __builtin_amdgcn_s_setprio(1); _Pragma("unroll") for (int m = 0; m < 4; ++m) _Pragma("unroll") for (int n = 0; n < 2; ++n) _Pragma("unroll") for (int k = 0; k < 2; ++k) \
;         acc[ai][bj][m][n] = __builtin_amdgcn_mfma_f32_16x16x32_bf16(Bt[n][k], At[m][k], acc[ai][bj][m][n], 0, 0, 0); __builtin_amdgcn_s_setprio(0); } while (0)
; #define PG8_WAIT_V(n) asm volatile("s_waitcnt vmcnt(" #n ")" ::: "memory")
; #define PG8_WAIT_L(n) asm volatile("s_waitcnt lgkmcnt(" #n ")" ::: "memory")
; #define PG8_BAR __builtin_amdgcn_s_barrier()
; #define PG8_SCHED __builtin_amdgcn_sched_barrier(0)
; template <class Epi, class Sched, bool ALIGN_EPI = false, bool SP2 = false>
; __device__ __forceinline__ void gemm_phase(PG8_LAS unsigned char* lds, const Gemm g, const Sched& S, const Epi& E) {
;     ...
;             PG8_WAIT_V(8); PG8_WAIT_L(0); PG8_BAR; PG8_MMA(0, 0, At, B0); PG8_MMA(0, 1, At, B1); PG8_BAR; PG8_SCHED;
;             PG8_LDA(At, 0, 1); PG8_STAGE(PG8_SB(0, 0), b2, voffB); PG8_STAGE(PG8_SB(0, 1), b2 + hstep, voffB); PG8_STAGE(PG8_SA(0, 0), a2, voffA);
;             PG8_WAIT_V(8); PG8_WAIT_L(0); PG8_BAR; PG8_MMA(1, 0, At, B0); PG8_MMA(1, 1, At, B1); PG8_BAR; PG8_SCHED;
	s_setprio 1
	s_waitcnt lgkmcnt(0)
	v_mfma_f32_16x16x32_bf16 v[124:127], v[144:147], v[186:189], v[124:127]
	v_mfma_f32_16x16x32_bf16 v[120:123], v[162:165], v[186:189], v[120:123]
	v_mfma_f32_16x16x32_bf16 v[116:119], v[144:147], v[194:197], v[116:119]
	v_mfma_f32_16x16x32_bf16 v[104:107], v[162:165], v[194:197], v[104:107]
	v_mfma_f32_16x16x32_bf16 v[92:95], v[144:147], v[208:211], v[92:95]
	v_mfma_f32_16x16x32_bf16 v[88:91], v[162:165], v[208:211], v[88:91]
	v_mfma_f32_16x16x32_bf16 v[76:79], v[144:147], v[216:219], v[76:79]
	v_mfma_f32_16x16x32_bf16 v[72:75], v[162:165], v[216:219], v[72:75]
	v_mfma_f32_16x16x32_bf16 v[124:127], v[158:161], v[190:193], v[124:127]
	v_mfma_f32_16x16x32_bf16 v[120:123], v[166:169], v[190:193], v[120:123]
	v_mfma_f32_16x16x32_bf16 v[116:119], v[158:161], v[204:207], v[116:119]
	v_mfma_f32_16x16x32_bf16 v[104:107], v[166:169], v[204:207], v[104:107]
	v_mfma_f32_16x16x32_bf16 v[92:95], v[158:161], v[212:215], v[92:95]
	v_mfma_f32_16x16x32_bf16 v[88:91], v[166:169], v[212:215], v[88:91]
	v_mfma_f32_16x16x32_bf16 v[76:79], v[158:161], v[220:223], v[76:79]
	v_mfma_f32_16x16x32_bf16 v[72:75], v[166:169], v[220:223], v[72:75]
	s_setprio 0
	s_setprio 1
	v_mfma_f32_16x16x32_bf16 v[112:115], v[170:173], v[186:189], v[112:115]
	v_mfma_f32_16x16x32_bf16 v[108:111], v[178:181], v[186:189], v[108:111]
	v_mfma_f32_16x16x32_bf16 v[100:103], v[170:173], v[194:197], v[100:103]
	v_mfma_f32_16x16x32_bf16 v[96:99], v[178:181], v[194:197], v[96:99]
	v_mfma_f32_16x16x32_bf16 v[84:87], v[170:173], v[208:211], v[84:87]
	v_mfma_f32_16x16x32_bf16 v[80:83], v[178:181], v[208:211], v[80:83]
	v_mfma_f32_16x16x32_bf16 v[68:71], v[170:173], v[216:219], v[68:71]
	v_mfma_f32_16x16x32_bf16 v[64:67], v[178:181], v[216:219], v[64:67]
	v_mfma_f32_16x16x32_bf16 v[112:115], v[174:177], v[190:193], v[112:115]
	v_mfma_f32_16x16x32_bf16 v[108:111], v[182:185], v[190:193], v[108:111]
	v_mfma_f32_16x16x32_bf16 v[100:103], v[174:177], v[204:207], v[100:103]
	v_mfma_f32_16x16x32_bf16 v[96:99], v[182:185], v[204:207], v[96:99]
	v_mfma_f32_16x16x32_bf16 v[84:87], v[174:177], v[212:215], v[84:87]
	v_mfma_f32_16x16x32_bf16 v[80:83], v[182:185], v[212:215], v[80:83]
	v_mfma_f32_16x16x32_bf16 v[68:71], v[174:177], v[220:223], v[68:71]
	v_mfma_f32_16x16x32_bf16 v[64:67], v[182:185], v[220:223], v[64:67]
	s_setprio 0
	s_barrier
	s_add_i32 s45, s36, s26
	v_lshl_add_u64 v[148:149], s[22:23], 0, v[132:133]
	s_mov_b32 m0, s45
	ds_read_b128 v[186:189], v155 offset:16384
	ds_read_b128 v[190:193], v155 offset:17408
	ds_read_b128 v[194:197], v155 offset:18432
	ds_read_b128 v[204:207], v155 offset:19456
	ds_read_b128 v[208:211], v155 offset:20480
	ds_read_b128 v[212:215], v155 offset:21504
	ds_read_b128 v[216:219], v155 offset:22528
	ds_read_b128 v[220:223], v155 offset:23552
	global_load_lds_dwordx4 v[148:149], off
	s_add_i32 m0, s45, 0x2000
	s_add_u32 s46, s22, 0x40000
	v_lshl_add_u64 v[198:199], s[22:23], 0, v[128:129]
	s_addc_u32 s47, s23, 0
	s_add_i32 s45, s37, s26
	global_load_lds_dwordx4 v[198:199], off
	v_lshl_add_u64 v[224:225], s[46:47], 0, v[132:133]
	s_mov_b32 m0, s45
	v_lshl_add_u64 v[226:227], s[24:25], 0, v[130:131]
	global_load_lds_dwordx4 v[224:225], off
	v_lshl_add_u64 v[224:225], s[46:47], 0, v[128:129]
	s_add_i32 m0, s45, 0x2000
	s_nop 0
	global_load_lds_dwordx4 v[224:225], off
	v_lshl_add_u64 v[224:225], s[24:25], 0, v[134:135]
	s_mov_b32 m0, s28
	s_nop 0
	global_load_lds_dwordx4 v[224:225], off
	s_mov_b32 m0, s29
	s_nop 0
	global_load_lds_dwordx4 v[226:227], off
	s_waitcnt vmcnt(8)
	s_waitcnt lgkmcnt(0)
	s_barrier
	s_setprio 1
	s_waitcnt lgkmcnt(0)
	v_mfma_f32_16x16x32_bf16 v[60:63], v[144:147], v[186:189], v[60:63]
	v_mfma_f32_16x16x32_bf16 v[56:59], v[162:165], v[186:189], v[56:59]
	v_mfma_f32_16x16x32_bf16 v[44:47], v[144:147], v[194:197], v[44:47]
	v_mfma_f32_16x16x32_bf16 v[40:43], v[162:165], v[194:197], v[40:43]
	v_mfma_f32_16x16x32_bf16 v[28:31], v[144:147], v[208:211], v[28:31]
	v_mfma_f32_16x16x32_bf16 v[24:27], v[162:165], v[208:211], v[24:27]
	v_mfma_f32_16x16x32_bf16 v[12:15], v[144:147], v[216:219], v[12:15]
	v_mfma_f32_16x16x32_bf16 v[8:11], v[162:165], v[216:219], v[8:11]
	v_mfma_f32_16x16x32_bf16 v[60:63], v[158:161], v[190:193], v[60:63]
	v_mfma_f32_16x16x32_bf16 v[56:59], v[166:169], v[190:193], v[56:59]
	v_mfma_f32_16x16x32_bf16 v[44:47], v[158:161], v[204:207], v[44:47]
	v_mfma_f32_16x16x32_bf16 v[40:43], v[166:169], v[204:207], v[40:43]
	v_mfma_f32_16x16x32_bf16 v[28:31], v[158:161], v[212:215], v[28:31]
	v_mfma_f32_16x16x32_bf16 v[24:27], v[166:169], v[212:215], v[24:27]
	v_mfma_f32_16x16x32_bf16 v[12:15], v[158:161], v[220:223], v[12:15]
	v_mfma_f32_16x16x32_bf16 v[8:11], v[166:169], v[220:223], v[8:11]
	s_setprio 0
	s_setprio 1
	v_mfma_f32_16x16x32_bf16 v[52:55], v[170:173], v[186:189], v[52:55]
	v_mfma_f32_16x16x32_bf16 v[48:51], v[178:181], v[186:189], v[48:51]
	v_mfma_f32_16x16x32_bf16 v[36:39], v[170:173], v[194:197], v[36:39]
	v_mfma_f32_16x16x32_bf16 v[32:35], v[178:181], v[194:197], v[32:35]
	v_mfma_f32_16x16x32_bf16 v[20:23], v[170:173], v[208:211], v[20:23]
	v_mfma_f32_16x16x32_bf16 v[16:19], v[178:181], v[208:211], v[16:19]
	v_mfma_f32_16x16x32_bf16 v[4:7], v[170:173], v[216:219], v[4:7]
	v_mfma_f32_16x16x32_bf16 v[0:3], v[178:181], v[216:219], v[0:3]
	v_mfma_f32_16x16x32_bf16 v[52:55], v[174:177], v[190:193], v[52:55]
	v_mfma_f32_16x16x32_bf16 v[48:51], v[182:185], v[190:193], v[48:51]
	v_mfma_f32_16x16x32_bf16 v[36:39], v[174:177], v[204:207], v[36:39]
	v_mfma_f32_16x16x32_bf16 v[32:35], v[182:185], v[204:207], v[32:35]
	v_mfma_f32_16x16x32_bf16 v[20:23], v[174:177], v[212:215], v[20:23]
	v_mfma_f32_16x16x32_bf16 v[16:19], v[182:185], v[212:215], v[16:19]
	v_mfma_f32_16x16x32_bf16 v[4:7], v[174:177], v[220:223], v[4:7]
	v_mfma_f32_16x16x32_bf16 v[0:3], v[182:185], v[220:223], v[0:3]
	s_setprio 0
	s_barrier
; #define PG8_STAGE(bufoff, gbase, voff) do { _Pragma("unroll") for (int _i = 0; _i < 2; ++_i) \
;         __builtin_amdgcn_global_load_lds((const unsigned*)((const char*)(gbase) + (voff)[_i]), (PG8_LAS unsigned*)(lds + (bufoff) + ldsw + _i * 8192), 16, 0, 0); } while (0)
; #define PG8_LDA(dst, b, h) do { _Pragma("unroll") for (int m = 0; m < 4; ++m) _Pragma("unroll") for (int k = 0; k < 2; ++k) dst[m][k] = *(const PG8_LAS bf16x8*)(lds + PG8_SA(b, h) + aoff + m * 2048 + k * 1024); } while (0)
; #define PG8_LDB(dst, b, h) do { _Pragma("unroll") for (int n = 0; n < 2; ++n) _Pragma("unroll") for (int k = 0; k < 2; ++k) dst[n][k] = *(const PG8_LAS bf16x8*)(lds + PG8_SB(b, h) + boff + n * 2048 + k * 1024); } while (0)
; #define PG8_MMA(ai, bj, At, Bt) do { __builtin_amdgcn_s_setprio(1); _Pragma("unroll") for (int m = 0; m < 4; ++m) _Pragma("unroll") for (int n = 0; n < 2; ++n) _Pragma("unroll") for (int k = 0; k < 2; ++k) \
;         acc[ai][bj][m][n] = __builtin_amdgcn_mfma_f32_16x16x32_bf16(Bt[n][k], At[m][k], acc[ai][bj][m][n], 0, 0, 0); __builtin_amdgcn_s_setprio(0); } while (0)
; #define PG8_WAIT_V(n) asm volatile("s_waitcnt vmcnt(" #n ")" ::: "memory")
; #define PG8_WAIT_L(n) asm volatile("s_waitcnt lgkmcnt(" #n ")" ::: "memory")
; #define PG8_BAR __builtin_amdgcn_s_barrier()
; #define PG8_SCHED __builtin_amdgcn_sched_barrier(0)
; template <class Epi, class Sched, bool ALIGN_EPI = false, bool SP2 = false>
; __device__ __forceinline__ void gemm_phase(PG8_LAS unsigned char* lds, const Gemm g, const Sched& S, const Epi& E) {
;     ...
;             PG8_LDB(B0, 1, 0); PG8_LDB(B1, 1, 1); PG8_SCHED; PG8_LDA(At, 1, 0); PG8_STAGE(PG8_SA(0, 1), a2 + hstep, voffA);
;             PG8_WAIT_V(8); PG8_WAIT_L(0); PG8_BAR; PG8_MMA(0, 0, At, B0); PG8_MMA(0, 1, At, B1); PG8_BAR; PG8_SCHED;
	s_add_i32 s45, 0, 0x18000
	v_add_u32_e32 v157, s45, v151
	s_add_i32 s46, 0, 0x1c000
	ds_read_b128 v[144:147], v157
	ds_read_b128 v[158:161], v157 offset:1024
	ds_read_b128 v[162:165], v157 offset:2048
	ds_read_b128 v[166:169], v157 offset:3072
	v_add_u32_e32 v157, s46, v151
	ds_read_b128 v[170:173], v157
	ds_read_b128 v[174:177], v157 offset:1024
	ds_read_b128 v[178:181], v157 offset:2048
	ds_read_b128 v[182:185], v157 offset:3072
	s_add_u32 s24, s24, 0x40000
	s_addc_u32 s25, s25, 0
	s_mov_b32 m0, s30
	v_lshl_add_u64 v[228:229], s[24:25], 0, v[134:135]
	ds_read_b128 v[186:189], v155 offset:32768
	ds_read_b128 v[190:193], v155 offset:33792
	ds_read_b128 v[194:197], v155 offset:34816
	ds_read_b128 v[204:207], v155 offset:35840
	ds_read_b128 v[208:211], v155 offset:36864
	ds_read_b128 v[212:215], v155 offset:37888
	ds_read_b128 v[216:219], v155 offset:38912
	ds_read_b128 v[220:223], v155 offset:39936
	global_load_lds_dwordx4 v[228:229], off
	v_lshl_add_u64 v[228:229], s[24:25], 0, v[130:131]
	s_mov_b32 m0, s31
	s_nop 0
	global_load_lds_dwordx4 v[228:229], off
	s_waitcnt vmcnt(8)
	s_waitcnt lgkmcnt(0)
	s_barrier
	s_setprio 1
	s_waitcnt lgkmcnt(0)
	v_mfma_f32_16x16x32_bf16 v[124:127], v[144:147], v[186:189], v[124:127]
	v_mfma_f32_16x16x32_bf16 v[120:123], v[162:165], v[186:189], v[120:123]
	v_mfma_f32_16x16x32_bf16 v[116:119], v[144:147], v[194:197], v[116:119]
	v_mfma_f32_16x16x32_bf16 v[104:107], v[162:165], v[194:197], v[104:107]
	v_mfma_f32_16x16x32_bf16 v[92:95], v[144:147], v[208:211], v[92:95]
	v_mfma_f32_16x16x32_bf16 v[88:91], v[162:165], v[208:211], v[88:91]
	v_mfma_f32_16x16x32_bf16 v[76:79], v[144:147], v[216:219], v[76:79]
	v_mfma_f32_16x16x32_bf16 v[72:75], v[162:165], v[216:219], v[72:75]
	v_mfma_f32_16x16x32_bf16 v[124:127], v[158:161], v[190:193], v[124:127]
	v_mfma_f32_16x16x32_bf16 v[120:123], v[166:169], v[190:193], v[120:123]
	v_mfma_f32_16x16x32_bf16 v[116:119], v[158:161], v[204:207], v[116:119]
	v_mfma_f32_16x16x32_bf16 v[104:107], v[166:169], v[204:207], v[104:107]
	v_mfma_f32_16x16x32_bf16 v[92:95], v[158:161], v[212:215], v[92:95]
	v_mfma_f32_16x16x32_bf16 v[88:91], v[166:169], v[212:215], v[88:91]
	v_mfma_f32_16x16x32_bf16 v[76:79], v[158:161], v[220:223], v[76:79]
	v_mfma_f32_16x16x32_bf16 v[72:75], v[166:169], v[220:223], v[72:75]
	s_setprio 0
	s_setprio 1
	v_mfma_f32_16x16x32_bf16 v[112:115], v[170:173], v[186:189], v[112:115]
	v_mfma_f32_16x16x32_bf16 v[108:111], v[178:181], v[186:189], v[108:111]
	v_mfma_f32_16x16x32_bf16 v[100:103], v[170:173], v[194:197], v[100:103]
	v_mfma_f32_16x16x32_bf16 v[96:99], v[178:181], v[194:197], v[96:99]
	v_mfma_f32_16x16x32_bf16 v[84:87], v[170:173], v[208:211], v[84:87]
	v_mfma_f32_16x16x32_bf16 v[80:83], v[178:181], v[208:211], v[80:83]
	v_mfma_f32_16x16x32_bf16 v[68:71], v[170:173], v[216:219], v[68:71]
	v_mfma_f32_16x16x32_bf16 v[64:67], v[178:181], v[216:219], v[64:67]
	v_mfma_f32_16x16x32_bf16 v[112:115], v[174:177], v[190:193], v[112:115]
	v_mfma_f32_16x16x32_bf16 v[108:111], v[182:185], v[190:193], v[108:111]
	v_mfma_f32_16x16x32_bf16 v[100:103], v[174:177], v[204:207], v[100:103]
	v_mfma_f32_16x16x32_bf16 v[96:99], v[182:185], v[204:207], v[96:99]
	v_mfma_f32_16x16x32_bf16 v[84:87], v[174:177], v[212:215], v[84:87]
	v_mfma_f32_16x16x32_bf16 v[80:83], v[182:185], v[212:215], v[80:83]
	v_mfma_f32_16x16x32_bf16 v[68:71], v[174:177], v[220:223], v[68:71]
	v_mfma_f32_16x16x32_bf16 v[64:67], v[182:185], v[220:223], v[64:67]
	s_setprio 0
	s_barrier
; #define PG8_STAGE(bufoff, gbase, voff) do { _Pragma("unroll") for (int _i = 0; _i < 2; ++_i) \
;         __builtin_amdgcn_global_load_lds((const unsigned*)((const char*)(gbase) + (voff)[_i]), (PG8_LAS unsigned*)(lds + (bufoff) + ldsw + _i * 8192), 16, 0, 0); } while (0)
; #define PG8_LDA(dst, b, h) do { _Pragma("unroll") for (int m = 0; m < 4; ++m) _Pragma("unroll") for (int k = 0; k < 2; ++k) dst[m][k] = *(const PG8_LAS bf16x8*)(lds + PG8_SA(b, h) + aoff + m * 2048 + k * 1024); } while (0)
; #define PG8_MMA(ai, bj, At, Bt) do { __builtin_amdgcn_s_setprio(1); _Pragma("unroll") for (int m = 0; m < 4; ++m) _Pragma("unroll") for (int n = 0; n < 2; ++n) _Pragma("unroll") for (int k = 0; k < 2; ++k) \
;         acc[ai][bj][m][n] = __builtin_amdgcn_mfma_f32_16x16x32_bf16(Bt[n][k], At[m][k], acc[ai][bj][m][n], 0, 0, 0); __builtin_amdgcn_s_setprio(0); } while (0)
; #define PG8_WAIT_V(n) asm volatile("s_waitcnt vmcnt(" #n ")" ::: "memory")
; #define PG8_WAIT_L(n) asm volatile("s_waitcnt lgkmcnt(" #n ")" ::: "memory")
; #define PG8_BAR __builtin_amdgcn_s_barrier()
; #define PG8_SCHED __builtin_amdgcn_sched_barrier(0)
; template <class Epi, class Sched, bool ALIGN_EPI = false, bool SP2 = false>
; __device__ __forceinline__ void gemm_phase(PG8_LAS unsigned char* lds, const Gemm g, const Sched& S, const Epi& E) {
;     ...
;             PG8_LDA(At, 1, 1); PG8_STAGE(PG8_SB(1, 0), b3, voffB); PG8_STAGE(PG8_SB(1, 1), b3 + hstep, voffB); PG8_STAGE(PG8_SA(1, 0), a3, voffA);
;             PG8_WAIT_V(8); PG8_WAIT_L(0); PG8_BAR; PG8_MMA(1, 0, At, B0); PG8_MMA(1, 1, At, B1); PG8_BAR; PG8_SCHED;
	s_add_i32 s24, s45, s26
	v_lshl_add_u64 v[148:149], v[148:149], 0, s[4:5]
	s_mov_b32 m0, s24
	ds_read_b128 v[186:189], v155 offset:49152
	ds_read_b128 v[190:193], v155 offset:50176
	ds_read_b128 v[194:197], v155 offset:51200
	ds_read_b128 v[204:207], v155 offset:52224
	ds_read_b128 v[208:211], v155 offset:53248
	ds_read_b128 v[212:215], v155 offset:54272
	ds_read_b128 v[216:219], v155 offset:55296
	ds_read_b128 v[220:223], v155 offset:56320
	global_load_lds_dwordx4 v[148:149], off
	s_add_i32 m0, s24, 0x2000
	s_add_u32 s22, s22, 0x40080
	v_lshl_add_u64 v[148:149], v[198:199], 0, s[4:5]
	s_addc_u32 s23, s23, 0
	s_add_i32 s24, s46, s26
	global_load_lds_dwordx4 v[148:149], off
	v_lshl_add_u64 v[148:149], s[22:23], 0, v[132:133]
	s_mov_b32 m0, s24
	s_nop 0
	global_load_lds_dwordx4 v[148:149], off
	v_lshl_add_u64 v[148:149], s[22:23], 0, v[128:129]
	s_add_i32 m0, s24, 0x2000
	s_nop 0
	global_load_lds_dwordx4 v[148:149], off
	v_lshl_add_u64 v[148:149], v[224:225], 0, s[4:5]
	s_mov_b32 m0, s34
	s_nop 0
	global_load_lds_dwordx4 v[148:149], off
	v_lshl_add_u64 v[148:149], v[226:227], 0, s[4:5]
	s_mov_b32 m0, s35
	s_nop 0
	global_load_lds_dwordx4 v[148:149], off
	s_waitcnt vmcnt(8)
	s_waitcnt lgkmcnt(0)
	s_barrier
	s_setprio 1
	s_waitcnt lgkmcnt(0)
	v_mfma_f32_16x16x32_bf16 v[60:63], v[144:147], v[186:189], v[60:63]
	v_mfma_f32_16x16x32_bf16 v[56:59], v[162:165], v[186:189], v[56:59]
	v_mfma_f32_16x16x32_bf16 v[44:47], v[144:147], v[194:197], v[44:47]
	v_mfma_f32_16x16x32_bf16 v[40:43], v[162:165], v[194:197], v[40:43]
	v_mfma_f32_16x16x32_bf16 v[28:31], v[144:147], v[208:211], v[28:31]
	v_mfma_f32_16x16x32_bf16 v[24:27], v[162:165], v[208:211], v[24:27]
	v_mfma_f32_16x16x32_bf16 v[12:15], v[144:147], v[216:219], v[12:15]
	v_mfma_f32_16x16x32_bf16 v[8:11], v[162:165], v[216:219], v[8:11]
	v_mfma_f32_16x16x32_bf16 v[60:63], v[158:161], v[190:193], v[60:63]
	v_mfma_f32_16x16x32_bf16 v[56:59], v[166:169], v[190:193], v[56:59]
	v_mfma_f32_16x16x32_bf16 v[44:47], v[158:161], v[204:207], v[44:47]
	v_mfma_f32_16x16x32_bf16 v[40:43], v[166:169], v[204:207], v[40:43]
	v_mfma_f32_16x16x32_bf16 v[28:31], v[158:161], v[212:215], v[28:31]
	v_mfma_f32_16x16x32_bf16 v[24:27], v[166:169], v[212:215], v[24:27]
	v_mfma_f32_16x16x32_bf16 v[12:15], v[158:161], v[220:223], v[12:15]
	v_mfma_f32_16x16x32_bf16 v[8:11], v[166:169], v[220:223], v[8:11]
	s_setprio 0
	s_setprio 1
	v_mfma_f32_16x16x32_bf16 v[52:55], v[170:173], v[186:189], v[52:55]
	v_mfma_f32_16x16x32_bf16 v[48:51], v[178:181], v[186:189], v[48:51]
	v_mfma_f32_16x16x32_bf16 v[36:39], v[170:173], v[194:197], v[36:39]
	v_mfma_f32_16x16x32_bf16 v[32:35], v[178:181], v[194:197], v[32:35]
	v_mfma_f32_16x16x32_bf16 v[20:23], v[170:173], v[208:211], v[20:23]
	v_mfma_f32_16x16x32_bf16 v[16:19], v[178:181], v[208:211], v[16:19]
	v_mfma_f32_16x16x32_bf16 v[4:7], v[170:173], v[216:219], v[4:7]
	v_mfma_f32_16x16x32_bf16 v[0:3], v[178:181], v[216:219], v[0:3]
	v_mfma_f32_16x16x32_bf16 v[52:55], v[174:177], v[190:193], v[52:55]
	v_mfma_f32_16x16x32_bf16 v[48:51], v[182:185], v[190:193], v[48:51]
	v_mfma_f32_16x16x32_bf16 v[36:39], v[174:177], v[204:207], v[36:39]
	v_mfma_f32_16x16x32_bf16 v[32:35], v[182:185], v[204:207], v[32:35]
	v_mfma_f32_16x16x32_bf16 v[20:23], v[174:177], v[212:215], v[20:23]
	v_mfma_f32_16x16x32_bf16 v[16:19], v[182:185], v[212:215], v[16:19]
	v_mfma_f32_16x16x32_bf16 v[4:7], v[174:177], v[220:223], v[4:7]
	v_mfma_f32_16x16x32_bf16 v[0:3], v[182:185], v[220:223], v[0:3]
	s_setprio 0
	s_barrier
	s_add_i32 s44, s44, 2
	s_add_u32 s20, s20, 0x100
	s_addc_u32 s21, s21, 0
	s_add_u32 s42, s42, 0x100
	s_addc_u32 s43, s43, 0
	s_cmp_gt_u32 s44, 13
	s_cbranch_scc0 .LBB0_1253
	s_and_b64 vcc, exec, s[6:7]
	s_cbranch_vccz .LBB0_1256
	s_barrier

; #define PG8_STAGE(bufoff, gbase, voff) do { _Pragma("unroll") for (int _i = 0; _i < 2; ++_i) \
;         __builtin_amdgcn_global_load_lds((const unsigned*)((const char*)(gbase) + (voff)[_i]), (PG8_LAS unsigned*)(lds + (bufoff) + ldsw + _i * 8192), 16, 0, 0); } while (0)
; #define PG8_LDA(dst, b, h) do { _Pragma("unroll") for (int m = 0; m < 4; ++m) _Pragma("unroll") for (int k = 0; k < 2; ++k) dst[m][k] = *(const PG8_LAS bf16x8*)(lds + PG8_SA(b, h) + aoff + m * 2048 + k * 1024); } while (0)
; #define PG8_LDB(dst, b, h) do { _Pragma("unroll") for (int n = 0; n < 2; ++n) _Pragma("unroll") for (int k = 0; k < 2; ++k) dst[n][k] = *(const PG8_LAS bf16x8*)(lds + PG8_SB(b, h) + boff + n * 2048 + k * 1024); } while (0)
; #define PG8_MMA(ai, bj, At, Bt) do { __builtin_amdgcn_s_setprio(1); _Pragma("unroll") for (int m = 0; m < 4; ++m) _Pragma("unroll") for (int n = 0; n < 2; ++n) _Pragma("unroll") for (int k = 0; k < 2; ++k) \
;         acc[ai][bj][m][n] = __builtin_amdgcn_mfma_f32_16x16x32_bf16(Bt[n][k], At[m][k], acc[ai][bj][m][n], 0, 0, 0); __builtin_amdgcn_s_setprio(0); } while (0)
; #define PG8_WAIT_V(n) asm volatile("s_waitcnt vmcnt(" #n ")" ::: "memory")
; #define PG8_WAIT_L(n) asm volatile("s_waitcnt lgkmcnt(" #n ")" ::: "memory")
; #define PG8_BAR __builtin_amdgcn_s_barrier()
; #define PG8_SCHED __builtin_amdgcn_sched_barrier(0)
; template <class Epi, class Sched, bool ALIGN_EPI = false, bool SP2 = false>
; __device__ __forceinline__ void gemm_phase(PG8_LAS unsigned char* lds, const Gemm g, const Sched& S, const Epi& E) {
;     ...
;             PG8_LDB(B0, 0, 0); PG8_LDB(B1, 0, 1); PG8_SCHED; PG8_LDA(At, 0, 0); PG8_STAGE(PG8_SA(1, 1), a1 + hstep, voffA);
;             PG8_WAIT_V(8); PG8_WAIT_L(0); PG8_BAR; PG8_MMA(0, 0, At, B0); PG8_MMA(0, 1, At, B1); PG8_BAR; PG8_SCHED;
;     ...
; #pragma unroll
;         for (int a = 0; a < 2; ++a)
; #pragma unroll
;             for (int b = 0; b < 2; ++b)
; #pragma unroll
;                 for (int m = 0; m < 4; ++m)
; #pragma unroll
;                     for (int n = 0; n < 2; ++n) acc[a][b][m][n] = (f32x4){0.f, 0.f, 0.f, 0.f};
.LBB0_1334:
	s_add_u32 s41, s20, 0x100
	v_mov_b32_e32 v0, 0
	s_addc_u32 s42, s21, 0
	s_mov_b32 s43, -2
	s_waitcnt lgkmcnt(0)
	v_mov_b32_e32 v1, v0
	v_mov_b32_e32 v2, v0
	v_mov_b32_e32 v3, v0
	v_mov_b32_e32 v4, v0
	v_mov_b32_e32 v5, v0
	v_mov_b32_e32 v6, v0
	v_mov_b32_e32 v7, v0
	v_mov_b32_e32 v16, v0
	v_mov_b32_e32 v17, v0
	v_mov_b32_e32 v18, v0
	v_mov_b32_e32 v19, v0
	v_mov_b32_e32 v20, v0
	v_mov_b32_e32 v21, v0
	v_mov_b32_e32 v22, v0
	v_mov_b32_e32 v23, v0
	v_mov_b32_e32 v32, v0
	v_mov_b32_e32 v33, v0
	v_mov_b32_e32 v34, v0
	v_mov_b32_e32 v35, v0
	v_mov_b32_e32 v36, v0
	v_mov_b32_e32 v37, v0
	v_mov_b32_e32 v38, v0
	v_mov_b32_e32 v39, v0
	v_mov_b32_e32 v48, v0
	v_mov_b32_e32 v49, v0
	v_mov_b32_e32 v50, v0
	v_mov_b32_e32 v51, v0
	v_mov_b32_e32 v52, v0
	v_mov_b32_e32 v53, v0
	v_mov_b32_e32 v54, v0
	v_mov_b32_e32 v55, v0
	v_mov_b32_e32 v8, v0
	v_mov_b32_e32 v9, v0
	v_mov_b32_e32 v10, v0
	v_mov_b32_e32 v11, v0
	v_mov_b32_e32 v12, v0
	v_mov_b32_e32 v13, v0
	v_mov_b32_e32 v14, v0
	v_mov_b32_e32 v15, v0
	v_mov_b32_e32 v24, v0
	v_mov_b32_e32 v25, v0
	v_mov_b32_e32 v26, v0
	v_mov_b32_e32 v27, v0
	v_mov_b32_e32 v28, v0
	v_mov_b32_e32 v29, v0
	v_mov_b32_e32 v30, v0
	v_mov_b32_e32 v31, v0
	v_mov_b32_e32 v40, v0
	v_mov_b32_e32 v41, v0
	v_mov_b32_e32 v42, v0
	v_mov_b32_e32 v43, v0
	v_mov_b32_e32 v44, v0
	v_mov_b32_e32 v45, v0
	v_mov_b32_e32 v46, v0
	v_mov_b32_e32 v47, v0
	v_mov_b32_e32 v56, v0
	v_mov_b32_e32 v57, v0
	v_mov_b32_e32 v58, v0
	v_mov_b32_e32 v59, v0
	v_mov_b32_e32 v60, v0
	v_mov_b32_e32 v61, v0
	v_mov_b32_e32 v62, v0
	v_mov_b32_e32 v63, v0
	v_mov_b32_e32 v64, v0
	v_mov_b32_e32 v65, v0
	v_mov_b32_e32 v66, v0
	v_mov_b32_e32 v67, v0
	v_mov_b32_e32 v68, v0
	v_mov_b32_e32 v69, v0
	v_mov_b32_e32 v70, v0
	v_mov_b32_e32 v71, v0
	v_mov_b32_e32 v80, v0
	v_mov_b32_e32 v81, v0
	v_mov_b32_e32 v82, v0
	v_mov_b32_e32 v83, v0
	v_mov_b32_e32 v84, v0
	v_mov_b32_e32 v85, v0
	v_mov_b32_e32 v86, v0
	v_mov_b32_e32 v87, v0
	v_mov_b32_e32 v96, v0
	v_mov_b32_e32 v97, v0
	v_mov_b32_e32 v98, v0
	v_mov_b32_e32 v99, v0
	v_mov_b32_e32 v100, v0
	v_mov_b32_e32 v101, v0
	v_mov_b32_e32 v102, v0
	v_mov_b32_e32 v103, v0
	v_mov_b32_e32 v112, v0
	v_mov_b32_e32 v113, v0
	v_mov_b32_e32 v114, v0
	v_mov_b32_e32 v115, v0
	v_mov_b32_e32 v116, v0
	v_mov_b32_e32 v117, v0
	v_mov_b32_e32 v118, v0
	v_mov_b32_e32 v119, v0
	v_mov_b32_e32 v72, v0
	v_mov_b32_e32 v73, v0
	v_mov_b32_e32 v74, v0
	v_mov_b32_e32 v75, v0
	v_mov_b32_e32 v76, v0
	v_mov_b32_e32 v77, v0
	v_mov_b32_e32 v78, v0
	v_mov_b32_e32 v79, v0
	v_mov_b32_e32 v88, v0
	v_mov_b32_e32 v89, v0
	v_mov_b32_e32 v90, v0
	v_mov_b32_e32 v91, v0
	v_mov_b32_e32 v92, v0
	v_mov_b32_e32 v93, v0
	v_mov_b32_e32 v94, v0
	v_mov_b32_e32 v95, v0
	v_mov_b32_e32 v104, v0
	v_mov_b32_e32 v105, v0
	v_mov_b32_e32 v106, v0
	v_mov_b32_e32 v107, v0
	v_mov_b32_e32 v108, v0
	v_mov_b32_e32 v109, v0
	v_mov_b32_e32 v110, v0
	v_mov_b32_e32 v111, v0
	v_mov_b32_e32 v120, v0
	v_mov_b32_e32 v121, v0
	v_mov_b32_e32 v122, v0
	v_mov_b32_e32 v123, v0
	v_mov_b32_e32 v124, v0
	v_mov_b32_e32 v125, v0
	v_mov_b32_e32 v126, v0
	v_mov_b32_e32 v127, v0
.LBB0_1335:
	ds_read_b128 v[128:131], v189
	ds_read_b128 v[132:135], v189 offset:1024
	ds_read_b128 v[136:139], v189 offset:2048
	ds_read_b128 v[140:143], v189 offset:3072
	ds_read_b128 v[144:147], v190
	ds_read_b128 v[148:151], v190 offset:1024
	ds_read_b128 v[168:171], v190 offset:2048
	ds_read_b128 v[172:175], v190 offset:3072
	s_add_u32 s20, s18, 0x100
	s_addc_u32 s21, s19, 0
	s_cmp_eq_u32 s43, 40
	s_cselect_b32 s25, s11, s21
	s_cselect_b32 s24, s10, s20
	s_cselect_b32 s23, s17, s42
	s_cselect_b32 s22, s16, s41
	v_lshl_add_u64 v[184:185], s[18:19], 0, v[160:161]
	s_add_i32 m0, s27, 0xc000
	ds_read_b128 v[176:179], v191
	ds_read_b128 v[180:183], v191 offset:1024
	ds_read_b128 v[192:195], v191 offset:2048
	ds_read_b128 v[196:199], v191 offset:3072
	ds_read_b128 v[204:207], v191 offset:4096
	ds_read_b128 v[208:211], v191 offset:5120
	ds_read_b128 v[212:215], v191 offset:6144
	ds_read_b128 v[216:219], v191 offset:7168
	global_load_lds_dwordx4 v[184:185], off
	v_lshl_add_u64 v[184:185], s[18:19], 0, v[162:163]
	s_add_i32 m0, s27, 0xe000
	s_nop 0
	global_load_lds_dwordx4 v[184:185], off
	s_waitcnt vmcnt(8)
	s_waitcnt lgkmcnt(0)
	s_barrier
	s_setprio 1
	s_waitcnt lgkmcnt(0)
	v_mfma_f32_16x16x32_bf16 v[124:127], v[128:131], v[176:179], v[124:127]
	v_mfma_f32_16x16x32_bf16 v[120:123], v[136:139], v[176:179], v[120:123]
	v_mfma_f32_16x16x32_bf16 v[108:111], v[128:131], v[192:195], v[108:111]
	v_mfma_f32_16x16x32_bf16 v[104:107], v[136:139], v[192:195], v[104:107]
	v_mfma_f32_16x16x32_bf16 v[92:95], v[128:131], v[204:207], v[92:95]
	v_mfma_f32_16x16x32_bf16 v[88:91], v[136:139], v[204:207], v[88:91]
	v_mfma_f32_16x16x32_bf16 v[76:79], v[128:131], v[212:215], v[76:79]
	v_mfma_f32_16x16x32_bf16 v[72:75], v[136:139], v[212:215], v[72:75]
	v_mfma_f32_16x16x32_bf16 v[124:127], v[132:135], v[180:183], v[124:127]
	v_mfma_f32_16x16x32_bf16 v[120:123], v[140:143], v[180:183], v[120:123]
	v_mfma_f32_16x16x32_bf16 v[108:111], v[132:135], v[196:199], v[108:111]
	v_mfma_f32_16x16x32_bf16 v[104:107], v[140:143], v[196:199], v[104:107]
	v_mfma_f32_16x16x32_bf16 v[92:95], v[132:135], v[208:211], v[92:95]
	v_mfma_f32_16x16x32_bf16 v[88:91], v[140:143], v[208:211], v[88:91]
	v_mfma_f32_16x16x32_bf16 v[76:79], v[132:135], v[216:219], v[76:79]
	v_mfma_f32_16x16x32_bf16 v[72:75], v[140:143], v[216:219], v[72:75]
	s_setprio 0
	s_setprio 1
	v_mfma_f32_16x16x32_bf16 v[116:119], v[144:147], v[176:179], v[116:119]
	v_mfma_f32_16x16x32_bf16 v[112:115], v[168:171], v[176:179], v[112:115]
	v_mfma_f32_16x16x32_bf16 v[100:103], v[144:147], v[192:195], v[100:103]
	v_mfma_f32_16x16x32_bf16 v[96:99], v[168:171], v[192:195], v[96:99]
	v_mfma_f32_16x16x32_bf16 v[84:87], v[144:147], v[204:207], v[84:87]
	v_mfma_f32_16x16x32_bf16 v[80:83], v[168:171], v[204:207], v[80:83]
	v_mfma_f32_16x16x32_bf16 v[68:71], v[144:147], v[212:215], v[68:71]
	v_mfma_f32_16x16x32_bf16 v[64:67], v[168:171], v[212:215], v[64:67]
	v_mfma_f32_16x16x32_bf16 v[116:119], v[148:151], v[180:183], v[116:119]
	v_mfma_f32_16x16x32_bf16 v[112:115], v[172:175], v[180:183], v[112:115]
	v_mfma_f32_16x16x32_bf16 v[100:103], v[148:151], v[196:199], v[100:103]
	v_mfma_f32_16x16x32_bf16 v[96:99], v[172:175], v[196:199], v[96:99]
	v_mfma_f32_16x16x32_bf16 v[84:87], v[148:151], v[208:211], v[84:87]
	v_mfma_f32_16x16x32_bf16 v[80:83], v[172:175], v[208:211], v[80:83]
	v_mfma_f32_16x16x32_bf16 v[68:71], v[148:151], v[216:219], v[68:71]
	v_mfma_f32_16x16x32_bf16 v[64:67], v[172:175], v[216:219], v[64:67]
	s_setprio 0
	s_barrier
; #define PG8_STAGE(bufoff, gbase, voff) do { _Pragma("unroll") for (int _i = 0; _i < 2; ++_i) \
;         __builtin_amdgcn_global_load_lds((const unsigned*)((const char*)(gbase) + (voff)[_i]), (PG8_LAS unsigned*)(lds + (bufoff) + ldsw + _i * 8192), 16, 0, 0); } while (0)
; #define PG8_LDA(dst, b, h) do { _Pragma("unroll") for (int m = 0; m < 4; ++m) _Pragma("unroll") for (int k = 0; k < 2; ++k) dst[m][k] = *(const PG8_LAS bf16x8*)(lds + PG8_SA(b, h) + aoff + m * 2048 + k * 1024); } while (0)
; #define PG8_LDB(dst, b, h) do { _Pragma("unroll") for (int n = 0; n < 2; ++n) _Pragma("unroll") for (int k = 0; k < 2; ++k) dst[n][k] = *(const PG8_LAS bf16x8*)(lds + PG8_SB(b, h) + boff + n * 2048 + k * 1024); } while (0)
; #define PG8_MMA(ai, bj, At, Bt) do { __builtin_amdgcn_s_setprio(1); _Pragma("unroll") for (int m = 0; m < 4; ++m) _Pragma("unroll") for (int n = 0; n < 2; ++n) _Pragma("unroll") for (int k = 0; k < 2; ++k) \
;         acc[ai][bj][m][n] = __builtin_amdgcn_mfma_f32_16x16x32_bf16(Bt[n][k], At[m][k], acc[ai][bj][m][n], 0, 0, 0); __builtin_amdgcn_s_setprio(0); } while (0)
; #define PG8_WAIT_V(n) asm volatile("s_waitcnt vmcnt(" #n ")" ::: "memory")
; #define PG8_WAIT_L(n) asm volatile("s_waitcnt lgkmcnt(" #n ")" ::: "memory")
; #define PG8_BAR __builtin_amdgcn_s_barrier()
; #define PG8_SCHED __builtin_amdgcn_sched_barrier(0)
; template <class Epi, class Sched, bool ALIGN_EPI = false, bool SP2 = false>
; __device__ __forceinline__ void gemm_phase(PG8_LAS unsigned char* lds, const Gemm g, const Sched& S, const Epi& E) {
;     ...
;             PG8_LDA(At, 0, 1); PG8_STAGE(PG8_SB(0, 0), b2, voffB); PG8_STAGE(PG8_SB(0, 1), b2 + hstep, voffB); PG8_STAGE(PG8_SA(0, 0), a2, voffA);
;             PG8_WAIT_V(8); PG8_WAIT_L(0); PG8_BAR; PG8_MMA(1, 0, At, B0); PG8_MMA(1, 1, At, B1); PG8_BAR; PG8_SCHED;
;             PG8_LDB(B0, 1, 0); PG8_LDB(B1, 1, 1); PG8_SCHED; PG8_LDA(At, 1, 0); PG8_STAGE(PG8_SA(0, 1), a2 + hstep, voffA);
;             PG8_WAIT_V(8); PG8_WAIT_L(0); PG8_BAR; PG8_MMA(0, 0, At, B0); PG8_MMA(0, 1, At, B1); PG8_BAR; PG8_SCHED;
	s_add_i32 s18, s35, s26
	v_lshl_add_u64 v[184:185], s[22:23], 0, v[154:155]
	s_mov_b32 m0, s18
	ds_read_b128 v[176:179], v191 offset:16384
	ds_read_b128 v[180:183], v191 offset:17408
	ds_read_b128 v[192:195], v191 offset:18432
	ds_read_b128 v[196:199], v191 offset:19456
	ds_read_b128 v[204:207], v191 offset:20480
	ds_read_b128 v[208:211], v191 offset:21504
	ds_read_b128 v[212:215], v191 offset:22528
	ds_read_b128 v[216:219], v191 offset:23552
	global_load_lds_dwordx4 v[184:185], off
	s_add_i32 m0, s18, 0x2000
	s_add_u32 s18, s22, 0xb0000
	v_lshl_add_u64 v[220:221], s[22:23], 0, v[158:159]
	s_addc_u32 s19, s23, 0
	s_add_i32 s44, s36, s26
	global_load_lds_dwordx4 v[220:221], off
	v_lshl_add_u64 v[222:223], s[18:19], 0, v[154:155]
	s_mov_b32 m0, s44
	v_lshl_add_u64 v[224:225], s[24:25], 0, v[156:157]
	global_load_lds_dwordx4 v[222:223], off
	v_lshl_add_u64 v[222:223], s[18:19], 0, v[158:159]
	s_add_i32 m0, s44, 0x2000
	s_nop 0
	global_load_lds_dwordx4 v[222:223], off
	v_lshl_add_u64 v[222:223], s[24:25], 0, v[152:153]
	s_mov_b32 m0, s27
	s_nop 0
	global_load_lds_dwordx4 v[222:223], off
	s_mov_b32 m0, s28
	s_nop 0
	global_load_lds_dwordx4 v[224:225], off
	s_waitcnt vmcnt(8)
	s_waitcnt lgkmcnt(0)
	s_barrier
	s_setprio 1
	s_waitcnt lgkmcnt(0)
	v_mfma_f32_16x16x32_bf16 v[60:63], v[128:131], v[176:179], v[60:63]
	v_mfma_f32_16x16x32_bf16 v[56:59], v[136:139], v[176:179], v[56:59]
	v_mfma_f32_16x16x32_bf16 v[44:47], v[128:131], v[192:195], v[44:47]
	v_mfma_f32_16x16x32_bf16 v[40:43], v[136:139], v[192:195], v[40:43]
	v_mfma_f32_16x16x32_bf16 v[28:31], v[128:131], v[204:207], v[28:31]
	v_mfma_f32_16x16x32_bf16 v[24:27], v[136:139], v[204:207], v[24:27]
	v_mfma_f32_16x16x32_bf16 v[12:15], v[128:131], v[212:215], v[12:15]
	v_mfma_f32_16x16x32_bf16 v[8:11], v[136:139], v[212:215], v[8:11]
	v_mfma_f32_16x16x32_bf16 v[60:63], v[132:135], v[180:183], v[60:63]
	v_mfma_f32_16x16x32_bf16 v[56:59], v[140:143], v[180:183], v[56:59]
	v_mfma_f32_16x16x32_bf16 v[44:47], v[132:135], v[196:199], v[44:47]
	v_mfma_f32_16x16x32_bf16 v[40:43], v[140:143], v[196:199], v[40:43]
	v_mfma_f32_16x16x32_bf16 v[28:31], v[132:135], v[208:211], v[28:31]
	v_mfma_f32_16x16x32_bf16 v[24:27], v[140:143], v[208:211], v[24:27]
	v_mfma_f32_16x16x32_bf16 v[12:15], v[132:135], v[216:219], v[12:15]
	v_mfma_f32_16x16x32_bf16 v[8:11], v[140:143], v[216:219], v[8:11]
	s_setprio 0
	s_setprio 1
	v_mfma_f32_16x16x32_bf16 v[52:55], v[144:147], v[176:179], v[52:55]
	v_mfma_f32_16x16x32_bf16 v[48:51], v[168:171], v[176:179], v[48:51]
	v_mfma_f32_16x16x32_bf16 v[36:39], v[144:147], v[192:195], v[36:39]
	v_mfma_f32_16x16x32_bf16 v[32:35], v[168:171], v[192:195], v[32:35]
	v_mfma_f32_16x16x32_bf16 v[20:23], v[144:147], v[204:207], v[20:23]
	v_mfma_f32_16x16x32_bf16 v[16:19], v[168:171], v[204:207], v[16:19]
	v_mfma_f32_16x16x32_bf16 v[4:7], v[144:147], v[212:215], v[4:7]
	v_mfma_f32_16x16x32_bf16 v[0:3], v[168:171], v[212:215], v[0:3]
	v_mfma_f32_16x16x32_bf16 v[52:55], v[148:151], v[180:183], v[52:55]
	v_mfma_f32_16x16x32_bf16 v[48:51], v[172:175], v[180:183], v[48:51]
	v_mfma_f32_16x16x32_bf16 v[36:39], v[148:151], v[196:199], v[36:39]
	v_mfma_f32_16x16x32_bf16 v[32:35], v[172:175], v[196:199], v[32:35]
	v_mfma_f32_16x16x32_bf16 v[20:23], v[148:151], v[208:211], v[20:23]
	v_mfma_f32_16x16x32_bf16 v[16:19], v[172:175], v[208:211], v[16:19]
	v_mfma_f32_16x16x32_bf16 v[4:7], v[148:151], v[216:219], v[4:7]
	v_mfma_f32_16x16x32_bf16 v[0:3], v[172:175], v[216:219], v[0:3]
	s_setprio 0
	s_barrier
	s_add_i32 s44, 0, 0x18000
	s_add_i32 s45, 0, 0x1c000
	v_add_u32_e32 v140, s44, v187
	v_add_u32_e32 v172, s45, v187
	ds_read_b128 v[128:131], v140
	ds_read_b128 v[132:135], v140 offset:1024
	ds_read_b128 v[136:139], v140 offset:2048
	ds_read_b128 v[140:143], v140 offset:3072
	ds_read_b128 v[144:147], v172
	ds_read_b128 v[148:151], v172 offset:1024
	ds_read_b128 v[168:171], v172 offset:2048
	ds_read_b128 v[172:175], v172 offset:3072
	s_add_u32 s18, s24, 0xb0000
	s_addc_u32 s19, s25, 0
	s_mov_b32 m0, s29
	v_lshl_add_u64 v[226:227], s[18:19], 0, v[152:153]
	ds_read_b128 v[176:179], v191 offset:32768
	ds_read_b128 v[180:183], v191 offset:33792
	ds_read_b128 v[192:195], v191 offset:34816
	ds_read_b128 v[196:199], v191 offset:35840
	ds_read_b128 v[204:207], v191 offset:36864
	ds_read_b128 v[208:211], v191 offset:37888
	ds_read_b128 v[212:215], v191 offset:38912
	ds_read_b128 v[216:219], v191 offset:39936
	global_load_lds_dwordx4 v[226:227], off
	v_lshl_add_u64 v[226:227], s[18:19], 0, v[156:157]
	s_mov_b32 m0, s30
	s_nop 0
	global_load_lds_dwordx4 v[226:227], off
	s_waitcnt vmcnt(8)
	s_waitcnt lgkmcnt(0)
	s_barrier
; #define PG8_STAGE(bufoff, gbase, voff) do { _Pragma("unroll") for (int _i = 0; _i < 2; ++_i) \
;         __builtin_amdgcn_global_load_lds((const unsigned*)((const char*)(gbase) + (voff)[_i]), (PG8_LAS unsigned*)(lds + (bufoff) + ldsw + _i * 8192), 16, 0, 0); } while (0)
; #define PG8_LDA(dst, b, h) do { _Pragma("unroll") for (int m = 0; m < 4; ++m) _Pragma("unroll") for (int k = 0; k < 2; ++k) dst[m][k] = *(const PG8_LAS bf16x8*)(lds + PG8_SA(b, h) + aoff + m * 2048 + k * 1024); } while (0)
; #define PG8_MMA(ai, bj, At, Bt) do { __builtin_amdgcn_s_setprio(1); _Pragma("unroll") for (int m = 0; m < 4; ++m) _Pragma("unroll") for (int n = 0; n < 2; ++n) _Pragma("unroll") for (int k = 0; k < 2; ++k) \
;         acc[ai][bj][m][n] = __builtin_amdgcn_mfma_f32_16x16x32_bf16(Bt[n][k], At[m][k], acc[ai][bj][m][n], 0, 0, 0); __builtin_amdgcn_s_setprio(0); } while (0)
; #define PG8_WAIT_V(n) asm volatile("s_waitcnt vmcnt(" #n ")" ::: "memory")
; #define PG8_WAIT_L(n) asm volatile("s_waitcnt lgkmcnt(" #n ")" ::: "memory")
; #define PG8_BAR __builtin_amdgcn_s_barrier()
; #define PG8_SCHED __builtin_amdgcn_sched_barrier(0)
; template <class Epi, class Sched, bool ALIGN_EPI = false, bool SP2 = false>
; __device__ __forceinline__ void gemm_phase(PG8_LAS unsigned char* lds, const Gemm g, const Sched& S, const Epi& E) {
;     ...
;             PG8_WAIT_V(8); PG8_WAIT_L(0); PG8_BAR; PG8_MMA(0, 0, At, B0); PG8_MMA(0, 1, At, B1); PG8_BAR; PG8_SCHED;
;             PG8_LDA(At, 1, 1); PG8_STAGE(PG8_SB(1, 0), b3, voffB); PG8_STAGE(PG8_SB(1, 1), b3 + hstep, voffB); PG8_STAGE(PG8_SA(1, 0), a3, voffA);
;             PG8_WAIT_V(8); PG8_WAIT_L(0); PG8_BAR; PG8_MMA(1, 0, At, B0); PG8_MMA(1, 1, At, B1); PG8_BAR; PG8_SCHED;
	s_setprio 1
	s_waitcnt lgkmcnt(0)
	v_mfma_f32_16x16x32_bf16 v[124:127], v[128:131], v[176:179], v[124:127]
	v_mfma_f32_16x16x32_bf16 v[120:123], v[136:139], v[176:179], v[120:123]
	v_mfma_f32_16x16x32_bf16 v[108:111], v[128:131], v[192:195], v[108:111]
	v_mfma_f32_16x16x32_bf16 v[104:107], v[136:139], v[192:195], v[104:107]
	v_mfma_f32_16x16x32_bf16 v[92:95], v[128:131], v[204:207], v[92:95]
	v_mfma_f32_16x16x32_bf16 v[88:91], v[136:139], v[204:207], v[88:91]
	v_mfma_f32_16x16x32_bf16 v[76:79], v[128:131], v[212:215], v[76:79]
	v_mfma_f32_16x16x32_bf16 v[72:75], v[136:139], v[212:215], v[72:75]
	v_mfma_f32_16x16x32_bf16 v[124:127], v[132:135], v[180:183], v[124:127]
	v_mfma_f32_16x16x32_bf16 v[120:123], v[140:143], v[180:183], v[120:123]
	v_mfma_f32_16x16x32_bf16 v[108:111], v[132:135], v[196:199], v[108:111]
	v_mfma_f32_16x16x32_bf16 v[104:107], v[140:143], v[196:199], v[104:107]
	v_mfma_f32_16x16x32_bf16 v[92:95], v[132:135], v[208:211], v[92:95]
	v_mfma_f32_16x16x32_bf16 v[88:91], v[140:143], v[208:211], v[88:91]
	v_mfma_f32_16x16x32_bf16 v[76:79], v[132:135], v[216:219], v[76:79]
	v_mfma_f32_16x16x32_bf16 v[72:75], v[140:143], v[216:219], v[72:75]
	s_setprio 0
	s_setprio 1
	v_mfma_f32_16x16x32_bf16 v[116:119], v[144:147], v[176:179], v[116:119]
	v_mfma_f32_16x16x32_bf16 v[112:115], v[168:171], v[176:179], v[112:115]
	v_mfma_f32_16x16x32_bf16 v[100:103], v[144:147], v[192:195], v[100:103]
	v_mfma_f32_16x16x32_bf16 v[96:99], v[168:171], v[192:195], v[96:99]
	v_mfma_f32_16x16x32_bf16 v[84:87], v[144:147], v[204:207], v[84:87]
	v_mfma_f32_16x16x32_bf16 v[80:83], v[168:171], v[204:207], v[80:83]
	v_mfma_f32_16x16x32_bf16 v[68:71], v[144:147], v[212:215], v[68:71]
	v_mfma_f32_16x16x32_bf16 v[64:67], v[168:171], v[212:215], v[64:67]
	v_mfma_f32_16x16x32_bf16 v[116:119], v[148:151], v[180:183], v[116:119]
	v_mfma_f32_16x16x32_bf16 v[112:115], v[172:175], v[180:183], v[112:115]
	v_mfma_f32_16x16x32_bf16 v[100:103], v[148:151], v[196:199], v[100:103]
	v_mfma_f32_16x16x32_bf16 v[96:99], v[172:175], v[196:199], v[96:99]
	v_mfma_f32_16x16x32_bf16 v[84:87], v[148:151], v[208:211], v[84:87]
	v_mfma_f32_16x16x32_bf16 v[80:83], v[172:175], v[208:211], v[80:83]
	v_mfma_f32_16x16x32_bf16 v[68:71], v[148:151], v[216:219], v[68:71]
	v_mfma_f32_16x16x32_bf16 v[64:67], v[172:175], v[216:219], v[64:67]
	s_setprio 0
	s_barrier
	s_add_i32 s18, s44, s26
	v_lshl_add_u64 v[184:185], v[184:185], 0, s[12:13]
	s_mov_b32 m0, s18
	ds_read_b128 v[176:179], v191 offset:49152
	ds_read_b128 v[180:183], v191 offset:50176
	ds_read_b128 v[192:195], v191 offset:51200
	ds_read_b128 v[196:199], v191 offset:52224
	ds_read_b128 v[204:207], v191 offset:53248
	ds_read_b128 v[208:211], v191 offset:54272
	ds_read_b128 v[212:215], v191 offset:55296
	ds_read_b128 v[216:219], v191 offset:56320
	global_load_lds_dwordx4 v[184:185], off
	s_add_i32 m0, s18, 0x2000
	s_add_u32 s18, s22, 0xb0080
	v_lshl_add_u64 v[184:185], v[220:221], 0, s[12:13]
	s_addc_u32 s19, s23, 0
	s_add_i32 s22, s45, s26
	global_load_lds_dwordx4 v[184:185], off
	v_lshl_add_u64 v[184:185], s[18:19], 0, v[154:155]
	s_mov_b32 m0, s22
	s_nop 0
	global_load_lds_dwordx4 v[184:185], off
	v_lshl_add_u64 v[184:185], s[18:19], 0, v[158:159]
	s_add_i32 m0, s22, 0x2000
	s_nop 0
	global_load_lds_dwordx4 v[184:185], off
	v_lshl_add_u64 v[184:185], v[222:223], 0, s[12:13]
	s_mov_b32 m0, s33
	s_nop 0
	global_load_lds_dwordx4 v[184:185], off
	v_lshl_add_u64 v[184:185], v[224:225], 0, s[12:13]
	s_mov_b32 m0, s34
	s_nop 0
	global_load_lds_dwordx4 v[184:185], off
	s_waitcnt vmcnt(8)
	s_waitcnt lgkmcnt(0)
	s_barrier
	s_setprio 1
	s_waitcnt lgkmcnt(0)
	v_mfma_f32_16x16x32_bf16 v[60:63], v[128:131], v[176:179], v[60:63]
	v_mfma_f32_16x16x32_bf16 v[56:59], v[136:139], v[176:179], v[56:59]
	v_mfma_f32_16x16x32_bf16 v[44:47], v[128:131], v[192:195], v[44:47]
	v_mfma_f32_16x16x32_bf16 v[40:43], v[136:139], v[192:195], v[40:43]
	v_mfma_f32_16x16x32_bf16 v[28:31], v[128:131], v[204:207], v[28:31]
	v_mfma_f32_16x16x32_bf16 v[24:27], v[136:139], v[204:207], v[24:27]
	v_mfma_f32_16x16x32_bf16 v[12:15], v[128:131], v[212:215], v[12:15]
	v_mfma_f32_16x16x32_bf16 v[8:11], v[136:139], v[212:215], v[8:11]
	v_mfma_f32_16x16x32_bf16 v[60:63], v[132:135], v[180:183], v[60:63]
	v_mfma_f32_16x16x32_bf16 v[56:59], v[140:143], v[180:183], v[56:59]
	v_mfma_f32_16x16x32_bf16 v[44:47], v[132:135], v[196:199], v[44:47]
	v_mfma_f32_16x16x32_bf16 v[40:43], v[140:143], v[196:199], v[40:43]
	v_mfma_f32_16x16x32_bf16 v[28:31], v[132:135], v[208:211], v[28:31]
	v_mfma_f32_16x16x32_bf16 v[24:27], v[140:143], v[208:211], v[24:27]
	v_mfma_f32_16x16x32_bf16 v[12:15], v[132:135], v[216:219], v[12:15]
	v_mfma_f32_16x16x32_bf16 v[8:11], v[140:143], v[216:219], v[8:11]
	s_setprio 0
	s_setprio 1
	v_mfma_f32_16x16x32_bf16 v[52:55], v[144:147], v[176:179], v[52:55]
	v_mfma_f32_16x16x32_bf16 v[48:51], v[168:171], v[176:179], v[48:51]
	v_mfma_f32_16x16x32_bf16 v[36:39], v[144:147], v[192:195], v[36:39]
	v_mfma_f32_16x16x32_bf16 v[32:35], v[168:171], v[192:195], v[32:35]
	v_mfma_f32_16x16x32_bf16 v[20:23], v[144:147], v[204:207], v[20:23]
	v_mfma_f32_16x16x32_bf16 v[16:19], v[168:171], v[204:207], v[16:19]
	v_mfma_f32_16x16x32_bf16 v[4:7], v[144:147], v[212:215], v[4:7]
	v_mfma_f32_16x16x32_bf16 v[0:3], v[168:171], v[212:215], v[0:3]
	v_mfma_f32_16x16x32_bf16 v[52:55], v[148:151], v[180:183], v[52:55]
	v_mfma_f32_16x16x32_bf16 v[48:51], v[172:175], v[180:183], v[48:51]
	v_mfma_f32_16x16x32_bf16 v[36:39], v[148:151], v[196:199], v[36:39]
	v_mfma_f32_16x16x32_bf16 v[32:35], v[172:175], v[196:199], v[32:35]
	v_mfma_f32_16x16x32_bf16 v[20:23], v[148:151], v[208:211], v[20:23]
	v_mfma_f32_16x16x32_bf16 v[16:19], v[172:175], v[208:211], v[16:19]
	v_mfma_f32_16x16x32_bf16 v[4:7], v[148:151], v[216:219], v[4:7]
	v_mfma_f32_16x16x32_bf16 v[0:3], v[172:175], v[216:219], v[0:3]
	s_setprio 0
	s_barrier
	s_add_i32 s43, s43, 2
	s_add_u32 s41, s41, 0x100
	s_addc_u32 s42, s42, 0
	s_cmp_gt_u32 s43, 41
	s_mov_b64 s[18:19], s[20:21]
	s_cbranch_scc0 .LBB0_1335
	s_and_b64 vcc, exec, s[14:15]
	s_cbranch_vccz .LBB0_1338
	s_barrier
